# hand-written token-shift tile with activation lanes gathered in one wave and a unified exp/rcp path; nt hint on its streaming row loads and stores; per-workgroup staggered insertion point of the non-a
# speedup vs baseline: 1.0141x; 1.0141x over previous
; DEV int vblock() { const int per = gridDim.x >> 3; return (blockIdx.x & 7) * per + (blockIdx.x >> 3); }
; DEV void branch_phase(const Params& p, int l, char* smem) {
;   const bool last = (l == 1);
;   for (int L = vblock(); L < 1088 + 544 + 1088; L += gridDim.x) {
.LBB0_217:
	s_andn2_b64 vcc, exec, s[0:1]
	s_mov_b64 s[78:79], 0
	s_cbranch_vccnz .LBB0_222
	v_readlane_b32 s58, v255, 44
	s_cmp_gt_i32 s47, 0
	s_mov_b64 s[78:79], -1
	v_readlane_b32 s59, v255, 45
	s_mov_b32 s52, 0x8800
	s_cbranch_scc0 .LBB0_618
	s_cmp_gt_i32 s47, 1
	s_mov_b64 s[0:1], -1
	s_cbranch_scc0 .LBB0_645
	v_writelane_b32 v255, s47, 50
	v_readlane_b32 s0, v252, 15
	v_writelane_b32 v255, s50, 51
	v_readlane_b32 s1, v252, 16
	s_andn2_b64 vcc, exec, s[0:1]
	v_writelane_b32 v255, s51, 52
	s_cbranch_vccnz .LBB0_644
	v_readlane_b32 s0, v255, 51
	v_readlane_b32 s1, v255, 52
	s_mov_b32 s40, s0
	s_mul_hi_i32 s36, s0, 0x5a00
	s_mul_i32 s37, s0, 0x5a00
	s_mul_hi_i32 s38, s0, 0xf800
	s_mul_i32 s39, s0, 0xf800
	s_lshl_b32 s0, s0, 9
	v_readlane_b32 s30, v255, 44
	s_ashr_i32 s1, s0, 31
	s_add_i32 s30, s30, 10
	s_cmp_lt_u32 s30, 23
	v_readlane_b32 s31, v255, 45
	s_cselect_b64 vcc, -1, 0
	s_lshl_b32 s30, s40, 7
	v_readlane_b32 s76, v251, 21
	s_lshl_b32 s96, s40, 6
	s_ashr_i32 s31, s30, 31
	v_readlane_b32 s84, v251, 29
	v_readlane_b32 s56, v254, 58
	v_readlane_b32 s77, v251, 22
	v_readlane_b32 s85, v251, 30
	s_add_u32 s76, s84, s37
	v_readlane_b32 s57, v254, 59
	v_readlane_b32 s58, v254, 60
	v_readlane_b32 s59, v254, 61
	v_readlane_b32 s60, v254, 62
	v_readlane_b32 s61, v254, 63
	v_readlane_b32 s62, v255, 0
	v_readlane_b32 s63, v255, 1
	v_readlane_b32 s64, v255, 2
	v_readlane_b32 s65, v255, 3
	v_readlane_b32 s66, v255, 4
	v_readlane_b32 s67, v255, 5
	s_addc_u32 s77, s85, s36
	s_lshl_b64 s[0:1], s[0:1], 2
	v_readlane_b32 s68, v255, 6
	v_readlane_b32 s69, v255, 7
	v_readlane_b32 s70, v255, 8
	v_readlane_b32 s71, v255, 9
	s_mov_b64 s[56:57], s[60:61]
	s_add_u32 s42, s56, s0
	s_mov_b64 s[58:59], s[62:63]
	s_addc_u32 s43, s57, s1
	s_add_u32 s44, s58, s0
	s_mov_b64 s[60:61], s[64:65]
	s_addc_u32 s45, s59, s1
	s_add_u32 s46, s60, s0
	v_readlane_b32 s80, v251, 25
	s_addc_u32 s47, s61, s1
	s_lshl_b64 s[0:1], s[30:31], 2
	v_readlane_b32 s81, v251, 26
	s_add_u32 s48, s80, s0
	v_mov_b32_e32 v0, 0x3eb60549
	v_mov_b32_e32 v1, 0x3e4ccccd
	s_mov_b64 s[62:63], s[66:67]
	s_mov_b64 s[64:65], s[68:69]
	s_mov_b64 s[66:67], s[70:71]
	s_addc_u32 s49, s81, s1
	v_readlane_b32 s0, v254, 57
	v_cndmask_b32_e32 v188, v0, v1, vcc
	v_readlane_b32 s64, v255, 38
	v_readlane_b32 s68, v255, 36
	v_readlane_b32 s66, v255, 34
	v_readlane_b32 s60, v255, 32
	s_add_u32 s50, s0, s39
	v_readlane_b32 s0, v255, 10
	v_sub_f32_e32 v189, 1.0, v188
	s_mov_b32 s71, 0x8000
	v_readlane_b32 s70, v255, 41
	v_readlane_b32 s65, v255, 39
	v_readlane_b32 s69, v255, 37
	v_readlane_b32 s67, v255, 35
	s_movk_i32 s41, 0x600
	v_readlane_b32 s61, v255, 33
	s_addc_u32 s51, s0, s38
	v_readlane_b32 s97, v254, 50
	v_readlane_b32 s40, v254, 49
	s_nop 3
	s_bfe_u32 s101, s40, 0x20003
	s_add_i32 s101, s101, 1
	s_cmp_eq_u32 s101, 0
	s_cbranch_scc0 .Lrot_st
	s_lshl_b32 s100, s92, 2
	s_add_i32 s40, s40, s100
	s_lshl_b32 s100, s33, 2
	s_add_i32 s97, s97, s100
.Lrot_st:
	v_readlane_b32 s78, v251, 23
	v_readlane_b32 s79, v251, 24
	v_readlane_b32 s82, v251, 27
	v_readlane_b32 s83, v251, 28
	v_readlane_b32 s86, v251, 31
	v_readlane_b32 s87, v251, 32
	v_readlane_b32 s88, v251, 33
	v_readlane_b32 s89, v251, 34
	v_readlane_b32 s90, v251, 35
	v_readlane_b32 s91, v251, 36
	s_branch .LBB0_306

; DEV int ltid() { int t = threadIdx.x; asm volatile("" : "+v"(t)); return t; }
; DEV int vblock() { const int per = gridDim.x >> 3; return (blockIdx.x & 7) * per + (blockIdx.x >> 3); }
; DEV void shift_tile(const Params& p, int l, int tile) {
;   const bf16_t* ZRW = (const bf16_t*)(p.ws + O_ZRW);
;   bf16_t* ZRS = (bf16_t*)(p.ws + O_ZRS);
;   const int r0 = tile * 32;
;   int s_lo, s_hi;
;   if (r0 < T_LAT) { s_lo = r0 & ~4095; s_hi = s_lo + SEQ; } else { s_lo = T_LAT + ((r0 - T_LAT) & ~255); s_hi = s_lo + CTXL; }
;   const int tid = ltid();
;   if (tid >= 480) return;
;   const int half = tid >= 240 ? 1 : 0, ch = tid - half * 240, col = ch * 8;
;   const int rb = r0 + half * 16;
;   u32x4 rows[18];
; #pragma unroll
;   for (int i = 0; i < 18; ++i) {
;     const int rr = rb - 1 + i;
;     rows[i] = (u32x4){0u, 0u, 0u, 0u};
;     if (rr >= s_lo && rr < s_hi) rows[i] = *(const u32x4*)(ZRW + (size_t)rr * 1920 + col);
;   }
;   const float* sw = p.rwkv_shift + (size_t)l * 3 * 1920 + col;
;   float w0[8], w1[8], w2[8];
; #pragma unroll
;   for (int j = 0; j < 8; ++j) { w0[j] = sw[j]; w1[j] = sw[1920 + j]; w2[j] = sw[3840 + j]; }
;   const int act = (col >= 1536 && col < 1664) ? 1 : (col >= 1792 ? 2 : 0);
; DEV void branch_phase(const Params& p, int l, char* smem) {
;   const bool last = (l == 1);
;   for (int L = vblock(); L < 1088 + 544 + 1088; L += gridDim.x) {
;     if (L < 1088) { if (!(last && L >= 1024)) attn_tile(p, l, L, smem); }
;     else if (L < 1632) { if (!(last && L - 1088 >= 512)) conv_tile(p, l, L - 1088, smem); }
;     else shift_tile(p, l, L - 1632);
.LBB0_305:
	s_lshr_b32 s100, s40, 8
	s_and_b32 s40, s40, 0xff
	s_bfe_u32 s101, s40, 0x20003
	s_add_i32 s101, s101, 1
	s_cmp_gt_u32 s100, 3
	s_cbranch_scc1 .Lrot_blk
	s_add_i32 s100, s100, 1
	s_cmp_eq_u32 s100, s101
	s_cbranch_scc1 .Lrot_to4
	s_cmp_eq_u32 s100, 4
	s_cbranch_scc1 .LBB0_644
	s_branch .Lrot_set
.Lrot_to4:
	s_mov_b32 s100, 4
	s_branch .Lrot_set
.Lrot_blk:
	s_add_i32 s100, s100, 1
	s_lshl_b32 vcc_lo, s100, 8
	s_add_i32 vcc_lo, vcc_lo, s40
	s_cmpk_gt_i32 vcc_lo, 0xa9f
	s_cbranch_scc0 .Lrot_set
	s_cmp_eq_u32 s101, 4
	s_cbranch_scc1 .LBB0_644
	s_mov_b32 s100, s101
.Lrot_set:
	s_lshl_b32 vcc_lo, s100, 8
	s_add_i32 s40, s40, vcc_lo
	v_readlane_b32 s97, v254, 50
	s_mul_i32 vcc_lo, s100, s33
	s_nop 3
	s_add_i32 s97, s97, vcc_lo
.LBB0_306:
	s_cmpk_gt_i32 s40, 0x43f
	s_mov_b64 s[0:1], -1
	s_cbranch_scc0 .LBB0_592
	s_cmpk_gt_u32 s40, 0x65f
	s_cbranch_scc0 .LBB0_570
	s_mov_b64 s[52:53], exec
	v_cmp_lt_u32_e32 vcc, 0x1bf, v226
	s_mov_b64 s[0:1], vcc
	v_cmp_gt_u32_e32 vcc, 0x1a0, v226
	s_or_b64 vcc, vcc, s[0:1]
	s_and_b64 exec, exec, vcc
	s_cbranch_execz .LBB0_569
	s_mov_b64 s[36:37], exec
	v_cmp_lt_u32_e32 vcc, 0xcf, v226
	v_cndmask_b32_e64 v123, 0, 1, vcc
	v_mul_u32_u24_e32 v122, 0xd0, v123
	v_sub_u32_e32 v122, v226, v122
	v_cmp_lt_u32_e32 vcc, 0xbf, v122
	v_cndmask_b32_e64 v134, 0, 16, vcc
	v_add_u32_e32 v122, v122, v134
	v_readfirstlane_b32 s101, v226
	s_cmpk_lt_u32 s101, 0x1c0
	s_cbranch_scc1 .Lsh_map
	v_bfe_u32 v123, v226, 5, 1
	v_and_b32_e32 v122, 31, v226
	v_cmp_lt_u32_e32 vcc, 15, v122
	v_mov_b32_e32 v134, 0xc0
	v_mov_b32_e32 v135, 0xd0
	v_cndmask_b32_e32 v134, v134, v135, vcc
	v_add_u32_e32 v122, v122, v134
.Lsh_map:
	v_lshlrev_b32_e32 v128, 4, v122
	s_add_i32 s100, s40, 0xfffff9a0
	s_lshl_b32 s100, s100, 5
	v_lshlrev_b32_e32 v134, 5, v122
	v_add_u32_e32 v135, 0x1e00, v134
	v_add_u32_e32 v130, 0x3c00, v134
	global_load_dwordx4 v[72:75], v134, s[76:77]
	global_load_dwordx4 v[76:79], v134, s[76:77] offset:16
	global_load_dwordx4 v[80:83], v135, s[76:77]
	global_load_dwordx4 v[84:87], v135, s[76:77] offset:16
	global_load_dwordx4 v[88:91], v130, s[76:77]
	global_load_dwordx4 v[92:95], v130, s[76:77] offset:16
	v_mul_u32_u24_e32 v129, 0xf000, v123
	v_add_u32_e32 v129, v129, v128
	v_readlane_b32 s0, v251, 49
	v_readlane_b32 s1, v251, 50
	s_sub_i32 s101, s100, 1
	s_mul_i32 s101, s101, 0xf00
	s_ashr_i32 s30, s101, 31
	s_add_u32 s0, s0, s101
	s_addc_u32 s1, s1, s30
	s_and_b32 s38, s100, 0xfffff000
	s_add_i32 s39, s38, 0x1000
	s_and_b32 s30, s100, 0xffffff00
	s_add_i32 s31, s30, 0x100
	s_cmp_lt_u32 s100, 0x8000
	s_cselect_b32 s38, s38, s30
	s_cselect_b32 s39, s39, s31
	s_cmp_lg_u32 s100, s38
	s_cselect_b32 s30, 1, 0
	s_add_i32 s101, s100, 32
	s_cmp_lg_u32 s101, s39
	s_cselect_b32 s31, 1, 0
	v_mov_b32_e32 v0, 0
	v_mov_b32_e32 v1, 0
	v_mov_b32_e32 v2, 0
	v_mov_b32_e32 v3, 0
	v_or_b32_e32 v134, s30, v123
	v_cmp_ne_u32_e32 vcc, 0, v134
	s_and_b64 exec, s[36:37], vcc
	global_load_dwordx4 v[0:3], v129, s[0:1] nt
	s_mov_b64 exec, s[36:37]
	s_add_u32 s0, s0, 0xf00
	s_addc_u32 s1, s1, 0
	global_load_dwordx4 v[4:7], v129, s[0:1] nt
	s_add_u32 s0, s0, 0xf00
	s_addc_u32 s1, s1, 0
	global_load_dwordx4 v[8:11], v129, s[0:1] nt
	s_add_u32 s0, s0, 0xf00
	s_addc_u32 s1, s1, 0
	global_load_dwordx4 v[12:15], v129, s[0:1] nt
	s_add_u32 s0, s0, 0xf00
	s_addc_u32 s1, s1, 0
	global_load_dwordx4 v[16:19], v129, s[0:1] nt
	s_add_u32 s0, s0, 0xf00
	s_addc_u32 s1, s1, 0
	global_load_dwordx4 v[20:23], v129, s[0:1] nt
	s_add_u32 s0, s0, 0xf00
	s_addc_u32 s1, s1, 0
	global_load_dwordx4 v[24:27], v129, s[0:1] nt
	s_add_u32 s0, s0, 0xf00
	s_addc_u32 s1, s1, 0
	global_load_dwordx4 v[28:31], v129, s[0:1] nt
	s_add_u32 s0, s0, 0xf00
	s_addc_u32 s1, s1, 0
	global_load_dwordx4 v[32:35], v129, s[0:1] nt
	s_add_u32 s0, s0, 0xf00
	s_addc_u32 s1, s1, 0
	global_load_dwordx4 v[36:39], v129, s[0:1] nt
	s_add_u32 s0, s0, 0xf00
	s_addc_u32 s1, s1, 0
	global_load_dwordx4 v[40:43], v129, s[0:1] nt
	s_add_u32 s0, s0, 0xf00
	s_addc_u32 s1, s1, 0
	global_load_dwordx4 v[44:47], v129, s[0:1] nt
	s_add_u32 s0, s0, 0xf00
	s_addc_u32 s1, s1, 0
	global_load_dwordx4 v[48:51], v129, s[0:1] nt
	s_add_u32 s0, s0, 0xf00
	s_addc_u32 s1, s1, 0
	global_load_dwordx4 v[52:55], v129, s[0:1] nt
	s_add_u32 s0, s0, 0xf00
	s_addc_u32 s1, s1, 0
	global_load_dwordx4 v[56:59], v129, s[0:1] nt
	s_add_u32 s0, s0, 0xf00
	s_addc_u32 s1, s1, 0
	global_load_dwordx4 v[60:63], v129, s[0:1] nt
	s_add_u32 s0, s0, 0xf00
	s_addc_u32 s1, s1, 0
	global_load_dwordx4 v[64:67], v129, s[0:1] nt
	s_add_u32 s0, s0, 0xf00
	s_addc_u32 s1, s1, 0
	v_mov_b32_e32 v68, 0
	v_mov_b32_e32 v69, 0
	v_mov_b32_e32 v70, 0
	v_mov_b32_e32 v71, 0
	v_xor_b32_e32 v134, 1, v123
	v_or_b32_e32 v134, s31, v134
	v_cmp_ne_u32_e32 vcc, 0, v134
	s_and_b64 exec, s[36:37], vcc
	global_load_dwordx4 v[68:71], v129, s[0:1] nt
	s_mov_b64 exec, s[36:37]
	v_lshl_add_u32 v130, v123, 4, s100
	v_mov_b32_e32 v126, 0xc00
	v_mov_b32_e32 v127, 0
	v_readlane_b32 s0, v253, 41
	v_readlane_b32 s1, v253, 42
	v_mov_b32_e32 v131, v128
	s_nop 0
	v_mov_b32_e32 v132, s0
	v_mov_b32_e32 v133, s1
	s_add_u32 s0, s74, 0x15400000
	s_addc_u32 s1, s75, 0
	v_cmp_lt_u32_e32 vcc, 0xbf, v122
	v_mov_b32_e32 v134, 0x200
	v_cndmask_b32_e32 v126, v126, v134, vcc
	v_mov_b32_e32 v134, s0
	v_cndmask_b32_e32 v132, v132, v134, vcc
	v_mov_b32_e32 v134, s1
	v_cndmask_b32_e32 v133, v133, v134, vcc
	v_add_u32_e32 v134, 0xfffff400, v128
	v_cndmask_b32_e32 v131, v131, v134, vcc
	s_add_u32 s0, s74, 0x1e6d0000
	s_addc_u32 s1, s75, 0
	v_cmp_lt_u32_e32 vcc, 0xdf, v122
	v_mov_b32_e32 v134, 0x100
	v_cndmask_b32_e32 v126, v126, v134, vcc
	v_mov_b32_e32 v134, s0
	v_cndmask_b32_e32 v132, v132, v134, vcc
	v_mov_b32_e32 v134, s1
	v_cndmask_b32_e32 v133, v133, v134, vcc
	v_add_u32_e32 v134, 0xfffff200, v128
	v_cndmask_b32_e32 v131, v131, v134, vcc
	v_mul_lo_u32 v134, v130, v126
	v_add_u32_e32 v134, v134, v131
	v_mov_b32_e32 v135, 0
	v_lshl_add_u64 v[124:125], v[134:135], 0, v[132:133]
	v_readfirstlane_b32 s101, v226
	s_cmpk_lt_u32 s101, 0x1c0
	s_cbranch_scc1 .Lsh_fast
	v_cmp_lt_u32_e32 vcc, 0xdf, v122
	v_mov_b32_e32 v128, 0x4038aa3b
	v_mov_b32_e32 v129, 0xbfb8aa3b
	v_cndmask_b32_e32 v130, v128, v129, vcc
	v_mov_b32_e32 v131, v130
	v_mov_b32_e32 v128, -2.0
	v_cndmask_b32_e64 v132, v128, 1.0, vcc
	v_mov_b32_e32 v133, v132
	v_cndmask_b32_e64 v134, 1.0, 0, vcc
	v_mov_b32_e32 v135, v134
	s_branch .Lsh_full
; DEV float lo_bf(unsigned u) { return __uint_as_float(u << 16); }
; DEV float hi_bf(unsigned u) { return __uint_as_float(u & 0xffff0000u); }
; DEV float sigmoidf_(float x) { return __builtin_amdgcn_rcpf(1.f + __expf(-x)); }
; DEV void shift_tile(const Params& p, int l, int tile) {
;     ...
; #pragma unroll
;   for (int i = 0; i < 16; ++i) {
;     const int row = rb + i;
;     const u32x4 pv = rows[i], cu = rows[i + 1], nx = rows[i + 2];
;     float y[8];
; #pragma unroll
;     for (int q = 0; q < 4; ++q) {
;       y[2 * q] = w0[2 * q] * lo_bf(pv[q]) + w1[2 * q] * lo_bf(cu[q]) + w2[2 * q] * lo_bf(nx[q]);
;       y[2 * q + 1] = w0[2 * q + 1] * hi_bf(pv[q]) + w1[2 * q + 1] * hi_bf(cu[q]) + w2[2 * q + 1] * hi_bf(nx[q]);
;     }
;     if (act == 1) {
; #pragma unroll
;       for (int j = 0; j < 8; ++j) y[j] = 1.f - 2.f * __builtin_amdgcn_rcpf(1.f + __expf(2.f * y[j]));
;     } else if (act == 2) {
; #pragma unroll
;       for (int j = 0; j < 8; ++j) y[j] = sigmoidf_(y[j]);
;     }
;     u32x4 o;
;     o[0] = pk2(y[0], y[1]); o[1] = pk2(y[2], y[3]); o[2] = pk2(y[4], y[5]); o[3] = pk2(y[6], y[7]);
;     if (col < 1536) *(u32x4*)(ZRS + (size_t)row * 1536 + col) = o;
.Lsh_fast:
	s_waitcnt vmcnt(15)
	v_lshlrev_b32_e32 v98, 16, v0
	v_and_b32_e32 v99, 0xffff0000, v0
	v_lshlrev_b32_e32 v100, 16, v1
	v_and_b32_e32 v101, 0xffff0000, v1
	v_lshlrev_b32_e32 v102, 16, v2
	v_and_b32_e32 v103, 0xffff0000, v2
	v_lshlrev_b32_e32 v104, 16, v3
	v_and_b32_e32 v105, 0xffff0000, v3
	v_lshlrev_b32_e32 v106, 16, v4
	v_and_b32_e32 v107, 0xffff0000, v4
	v_lshlrev_b32_e32 v108, 16, v5
	v_and_b32_e32 v109, 0xffff0000, v5
	v_lshlrev_b32_e32 v110, 16, v6
	v_and_b32_e32 v111, 0xffff0000, v6
	v_lshlrev_b32_e32 v112, 16, v7
	v_and_b32_e32 v113, 0xffff0000, v7
	v_lshlrev_b32_e32 v114, 16, v8
	v_and_b32_e32 v115, 0xffff0000, v8
	v_lshlrev_b32_e32 v116, 16, v9
	v_and_b32_e32 v117, 0xffff0000, v9
	v_lshlrev_b32_e32 v118, 16, v10
	v_and_b32_e32 v119, 0xffff0000, v10
	v_lshlrev_b32_e32 v120, 16, v11
	v_and_b32_e32 v121, 0xffff0000, v11
	v_pk_mul_f32 v[98:99], v[72:73], v[98:99]
	v_pk_mul_f32 v[100:101], v[74:75], v[100:101]
	v_pk_mul_f32 v[102:103], v[76:77], v[102:103]
	v_pk_mul_f32 v[104:105], v[78:79], v[104:105]
	v_pk_fma_f32 v[98:99], v[80:81], v[106:107], v[98:99]
	v_pk_fma_f32 v[100:101], v[82:83], v[108:109], v[100:101]
	v_pk_fma_f32 v[102:103], v[84:85], v[110:111], v[102:103]
	v_pk_fma_f32 v[104:105], v[86:87], v[112:113], v[104:105]
	v_pk_fma_f32 v[98:99], v[88:89], v[114:115], v[98:99]
	v_pk_fma_f32 v[100:101], v[90:91], v[116:117], v[100:101]
	v_pk_fma_f32 v[102:103], v[92:93], v[118:119], v[102:103]
	v_pk_fma_f32 v[104:105], v[94:95], v[120:121], v[104:105]
	v_cvt_pk_bf16_f32 v0, v98, v99
	v_cvt_pk_bf16_f32 v1, v100, v101
	v_cvt_pk_bf16_f32 v2, v102, v103
	v_cvt_pk_bf16_f32 v3, v104, v105
	global_store_dwordx4 v[124:125], v[0:3], off nt
	v_lshl_add_u64 v[124:125], v[126:127], 0, v[124:125]
	s_waitcnt vmcnt(15)
	v_lshlrev_b32_e32 v98, 16, v12
	v_and_b32_e32 v99, 0xffff0000, v12
	v_lshlrev_b32_e32 v100, 16, v13
	v_and_b32_e32 v101, 0xffff0000, v13
	v_lshlrev_b32_e32 v102, 16, v14
	v_and_b32_e32 v103, 0xffff0000, v14
	v_lshlrev_b32_e32 v104, 16, v15
	v_and_b32_e32 v105, 0xffff0000, v15
	v_pk_mul_f32 v[106:107], v[72:73], v[106:107]
	v_pk_mul_f32 v[108:109], v[74:75], v[108:109]
	v_pk_mul_f32 v[110:111], v[76:77], v[110:111]
	v_pk_mul_f32 v[112:113], v[78:79], v[112:113]
	v_pk_fma_f32 v[106:107], v[80:81], v[114:115], v[106:107]
	v_pk_fma_f32 v[108:109], v[82:83], v[116:117], v[108:109]
	v_pk_fma_f32 v[110:111], v[84:85], v[118:119], v[110:111]
	v_pk_fma_f32 v[112:113], v[86:87], v[120:121], v[112:113]
	v_pk_fma_f32 v[106:107], v[88:89], v[98:99], v[106:107]
	v_pk_fma_f32 v[108:109], v[90:91], v[100:101], v[108:109]
	v_pk_fma_f32 v[110:111], v[92:93], v[102:103], v[110:111]
	v_pk_fma_f32 v[112:113], v[94:95], v[104:105], v[112:113]
	v_cvt_pk_bf16_f32 v4, v106, v107
	v_cvt_pk_bf16_f32 v5, v108, v109
	v_cvt_pk_bf16_f32 v6, v110, v111
	v_cvt_pk_bf16_f32 v7, v112, v113
	global_store_dwordx4 v[124:125], v[4:7], off nt
	v_lshl_add_u64 v[124:125], v[126:127], 0, v[124:125]
	s_waitcnt vmcnt(15)
	v_lshlrev_b32_e32 v106, 16, v16
	v_and_b32_e32 v107, 0xffff0000, v16
	v_lshlrev_b32_e32 v108, 16, v17
	v_and_b32_e32 v109, 0xffff0000, v17
	v_lshlrev_b32_e32 v110, 16, v18
	v_and_b32_e32 v111, 0xffff0000, v18
	v_lshlrev_b32_e32 v112, 16, v19
	v_and_b32_e32 v113, 0xffff0000, v19
	v_pk_mul_f32 v[114:115], v[72:73], v[114:115]
	v_pk_mul_f32 v[116:117], v[74:75], v[116:117]
	v_pk_mul_f32 v[118:119], v[76:77], v[118:119]
	v_pk_mul_f32 v[120:121], v[78:79], v[120:121]
	v_pk_fma_f32 v[114:115], v[80:81], v[98:99], v[114:115]
	v_pk_fma_f32 v[116:117], v[82:83], v[100:101], v[116:117]
	v_pk_fma_f32 v[118:119], v[84:85], v[102:103], v[118:119]
	v_pk_fma_f32 v[120:121], v[86:87], v[104:105], v[120:121]
	v_pk_fma_f32 v[114:115], v[88:89], v[106:107], v[114:115]
	v_pk_fma_f32 v[116:117], v[90:91], v[108:109], v[116:117]
	v_pk_fma_f32 v[118:119], v[92:93], v[110:111], v[118:119]
	v_pk_fma_f32 v[120:121], v[94:95], v[112:113], v[120:121]
	v_cvt_pk_bf16_f32 v8, v114, v115
	v_cvt_pk_bf16_f32 v9, v116, v117
	v_cvt_pk_bf16_f32 v10, v118, v119
	v_cvt_pk_bf16_f32 v11, v120, v121
	global_store_dwordx4 v[124:125], v[8:11], off nt
	v_lshl_add_u64 v[124:125], v[126:127], 0, v[124:125]
	s_waitcnt vmcnt(15)
	v_lshlrev_b32_e32 v114, 16, v20
	v_and_b32_e32 v115, 0xffff0000, v20
	v_lshlrev_b32_e32 v116, 16, v21
	v_and_b32_e32 v117, 0xffff0000, v21
	v_lshlrev_b32_e32 v118, 16, v22
	v_and_b32_e32 v119, 0xffff0000, v22
	v_lshlrev_b32_e32 v120, 16, v23
	v_and_b32_e32 v121, 0xffff0000, v23
	v_pk_mul_f32 v[98:99], v[72:73], v[98:99]
	v_pk_mul_f32 v[100:101], v[74:75], v[100:101]
	v_pk_mul_f32 v[102:103], v[76:77], v[102:103]
	v_pk_mul_f32 v[104:105], v[78:79], v[104:105]
	v_pk_fma_f32 v[98:99], v[80:81], v[106:107], v[98:99]
	v_pk_fma_f32 v[100:101], v[82:83], v[108:109], v[100:101]
	v_pk_fma_f32 v[102:103], v[84:85], v[110:111], v[102:103]
	v_pk_fma_f32 v[104:105], v[86:87], v[112:113], v[104:105]
	v_pk_fma_f32 v[98:99], v[88:89], v[114:115], v[98:99]
	v_pk_fma_f32 v[100:101], v[90:91], v[116:117], v[100:101]
	v_pk_fma_f32 v[102:103], v[92:93], v[118:119], v[102:103]
	v_pk_fma_f32 v[104:105], v[94:95], v[120:121], v[104:105]
	v_cvt_pk_bf16_f32 v12, v98, v99
	v_cvt_pk_bf16_f32 v13, v100, v101
	v_cvt_pk_bf16_f32 v14, v102, v103
	v_cvt_pk_bf16_f32 v15, v104, v105
	global_store_dwordx4 v[124:125], v[12:15], off nt
	v_lshl_add_u64 v[124:125], v[126:127], 0, v[124:125]
	s_waitcnt vmcnt(15)
; DEV float lo_bf(unsigned u) { return __uint_as_float(u << 16); }
; DEV float hi_bf(unsigned u) { return __uint_as_float(u & 0xffff0000u); }
; DEV float sigmoidf_(float x) { return __builtin_amdgcn_rcpf(1.f + __expf(-x)); }
; DEV void shift_tile(const Params& p, int l, int tile) {
;     ...
; #pragma unroll
;   for (int i = 0; i < 16; ++i) {
;     const int row = rb + i;
;     const u32x4 pv = rows[i], cu = rows[i + 1], nx = rows[i + 2];
;     float y[8];
; #pragma unroll
;     for (int q = 0; q < 4; ++q) {
;       y[2 * q] = w0[2 * q] * lo_bf(pv[q]) + w1[2 * q] * lo_bf(cu[q]) + w2[2 * q] * lo_bf(nx[q]);
;       y[2 * q + 1] = w0[2 * q + 1] * hi_bf(pv[q]) + w1[2 * q + 1] * hi_bf(cu[q]) + w2[2 * q + 1] * hi_bf(nx[q]);
;     }
;     if (act == 1) {
; #pragma unroll
;       for (int j = 0; j < 8; ++j) y[j] = 1.f - 2.f * __builtin_amdgcn_rcpf(1.f + __expf(2.f * y[j]));
;     } else if (act == 2) {
; #pragma unroll
;       for (int j = 0; j < 8; ++j) y[j] = sigmoidf_(y[j]);
;     }
;     u32x4 o;
;     o[0] = pk2(y[0], y[1]); o[1] = pk2(y[2], y[3]); o[2] = pk2(y[4], y[5]); o[3] = pk2(y[6], y[7]);
;     if (col < 1536) *(u32x4*)(ZRS + (size_t)row * 1536 + col) = o;
	v_lshlrev_b32_e32 v98, 16, v24
	v_and_b32_e32 v99, 0xffff0000, v24
	v_lshlrev_b32_e32 v100, 16, v25
	v_and_b32_e32 v101, 0xffff0000, v25
	v_lshlrev_b32_e32 v102, 16, v26
	v_and_b32_e32 v103, 0xffff0000, v26
	v_lshlrev_b32_e32 v104, 16, v27
	v_and_b32_e32 v105, 0xffff0000, v27
	v_pk_mul_f32 v[106:107], v[72:73], v[106:107]
	v_pk_mul_f32 v[108:109], v[74:75], v[108:109]
	v_pk_mul_f32 v[110:111], v[76:77], v[110:111]
	v_pk_mul_f32 v[112:113], v[78:79], v[112:113]
	v_pk_fma_f32 v[106:107], v[80:81], v[114:115], v[106:107]
	v_pk_fma_f32 v[108:109], v[82:83], v[116:117], v[108:109]
	v_pk_fma_f32 v[110:111], v[84:85], v[118:119], v[110:111]
	v_pk_fma_f32 v[112:113], v[86:87], v[120:121], v[112:113]
	v_pk_fma_f32 v[106:107], v[88:89], v[98:99], v[106:107]
	v_pk_fma_f32 v[108:109], v[90:91], v[100:101], v[108:109]
	v_pk_fma_f32 v[110:111], v[92:93], v[102:103], v[110:111]
	v_pk_fma_f32 v[112:113], v[94:95], v[104:105], v[112:113]
	v_cvt_pk_bf16_f32 v16, v106, v107
	v_cvt_pk_bf16_f32 v17, v108, v109
	v_cvt_pk_bf16_f32 v18, v110, v111
	v_cvt_pk_bf16_f32 v19, v112, v113
	global_store_dwordx4 v[124:125], v[16:19], off nt
	v_lshl_add_u64 v[124:125], v[126:127], 0, v[124:125]
	s_waitcnt vmcnt(15)
	v_lshlrev_b32_e32 v106, 16, v28
	v_and_b32_e32 v107, 0xffff0000, v28
	v_lshlrev_b32_e32 v108, 16, v29
	v_and_b32_e32 v109, 0xffff0000, v29
	v_lshlrev_b32_e32 v110, 16, v30
	v_and_b32_e32 v111, 0xffff0000, v30
	v_lshlrev_b32_e32 v112, 16, v31
	v_and_b32_e32 v113, 0xffff0000, v31
	v_pk_mul_f32 v[114:115], v[72:73], v[114:115]
	v_pk_mul_f32 v[116:117], v[74:75], v[116:117]
	v_pk_mul_f32 v[118:119], v[76:77], v[118:119]
	v_pk_mul_f32 v[120:121], v[78:79], v[120:121]
	v_pk_fma_f32 v[114:115], v[80:81], v[98:99], v[114:115]
	v_pk_fma_f32 v[116:117], v[82:83], v[100:101], v[116:117]
	v_pk_fma_f32 v[118:119], v[84:85], v[102:103], v[118:119]
	v_pk_fma_f32 v[120:121], v[86:87], v[104:105], v[120:121]
	v_pk_fma_f32 v[114:115], v[88:89], v[106:107], v[114:115]
	v_pk_fma_f32 v[116:117], v[90:91], v[108:109], v[116:117]
	v_pk_fma_f32 v[118:119], v[92:93], v[110:111], v[118:119]
	v_pk_fma_f32 v[120:121], v[94:95], v[112:113], v[120:121]
	v_cvt_pk_bf16_f32 v20, v114, v115
	v_cvt_pk_bf16_f32 v21, v116, v117
	v_cvt_pk_bf16_f32 v22, v118, v119
	v_cvt_pk_bf16_f32 v23, v120, v121
	global_store_dwordx4 v[124:125], v[20:23], off nt
	v_lshl_add_u64 v[124:125], v[126:127], 0, v[124:125]
	s_waitcnt vmcnt(15)
	v_lshlrev_b32_e32 v114, 16, v32
	v_and_b32_e32 v115, 0xffff0000, v32
	v_lshlrev_b32_e32 v116, 16, v33
	v_and_b32_e32 v117, 0xffff0000, v33
	v_lshlrev_b32_e32 v118, 16, v34
	v_and_b32_e32 v119, 0xffff0000, v34
	v_lshlrev_b32_e32 v120, 16, v35
	v_and_b32_e32 v121, 0xffff0000, v35
	v_pk_mul_f32 v[98:99], v[72:73], v[98:99]
	v_pk_mul_f32 v[100:101], v[74:75], v[100:101]
	v_pk_mul_f32 v[102:103], v[76:77], v[102:103]
	v_pk_mul_f32 v[104:105], v[78:79], v[104:105]
	v_pk_fma_f32 v[98:99], v[80:81], v[106:107], v[98:99]
	v_pk_fma_f32 v[100:101], v[82:83], v[108:109], v[100:101]
	v_pk_fma_f32 v[102:103], v[84:85], v[110:111], v[102:103]
	v_pk_fma_f32 v[104:105], v[86:87], v[112:113], v[104:105]
	v_pk_fma_f32 v[98:99], v[88:89], v[114:115], v[98:99]
	v_pk_fma_f32 v[100:101], v[90:91], v[116:117], v[100:101]
	v_pk_fma_f32 v[102:103], v[92:93], v[118:119], v[102:103]
	v_pk_fma_f32 v[104:105], v[94:95], v[120:121], v[104:105]
	v_cvt_pk_bf16_f32 v24, v98, v99
	v_cvt_pk_bf16_f32 v25, v100, v101
	v_cvt_pk_bf16_f32 v26, v102, v103
	v_cvt_pk_bf16_f32 v27, v104, v105
	global_store_dwordx4 v[124:125], v[24:27], off nt
	v_lshl_add_u64 v[124:125], v[126:127], 0, v[124:125]
	s_waitcnt vmcnt(15)
	v_lshlrev_b32_e32 v98, 16, v36
	v_and_b32_e32 v99, 0xffff0000, v36
	v_lshlrev_b32_e32 v100, 16, v37
	v_and_b32_e32 v101, 0xffff0000, v37
	v_lshlrev_b32_e32 v102, 16, v38
	v_and_b32_e32 v103, 0xffff0000, v38
	v_lshlrev_b32_e32 v104, 16, v39
	v_and_b32_e32 v105, 0xffff0000, v39
	v_pk_mul_f32 v[106:107], v[72:73], v[106:107]
	v_pk_mul_f32 v[108:109], v[74:75], v[108:109]
	v_pk_mul_f32 v[110:111], v[76:77], v[110:111]
	v_pk_mul_f32 v[112:113], v[78:79], v[112:113]
	v_pk_fma_f32 v[106:107], v[80:81], v[114:115], v[106:107]
	v_pk_fma_f32 v[108:109], v[82:83], v[116:117], v[108:109]
	v_pk_fma_f32 v[110:111], v[84:85], v[118:119], v[110:111]
	v_pk_fma_f32 v[112:113], v[86:87], v[120:121], v[112:113]
	v_pk_fma_f32 v[106:107], v[88:89], v[98:99], v[106:107]
	v_pk_fma_f32 v[108:109], v[90:91], v[100:101], v[108:109]
	v_pk_fma_f32 v[110:111], v[92:93], v[102:103], v[110:111]
	v_pk_fma_f32 v[112:113], v[94:95], v[104:105], v[112:113]
	v_cvt_pk_bf16_f32 v28, v106, v107
	v_cvt_pk_bf16_f32 v29, v108, v109
	v_cvt_pk_bf16_f32 v30, v110, v111
	v_cvt_pk_bf16_f32 v31, v112, v113
	global_store_dwordx4 v[124:125], v[28:31], off nt
	v_lshl_add_u64 v[124:125], v[126:127], 0, v[124:125]
	s_waitcnt vmcnt(15)
	v_lshlrev_b32_e32 v106, 16, v40
	v_and_b32_e32 v107, 0xffff0000, v40
	v_lshlrev_b32_e32 v108, 16, v41
	v_and_b32_e32 v109, 0xffff0000, v41
	v_lshlrev_b32_e32 v110, 16, v42
	v_and_b32_e32 v111, 0xffff0000, v42
	v_lshlrev_b32_e32 v112, 16, v43
	v_and_b32_e32 v113, 0xffff0000, v43
	v_pk_mul_f32 v[114:115], v[72:73], v[114:115]
	v_pk_mul_f32 v[116:117], v[74:75], v[116:117]
	v_pk_mul_f32 v[118:119], v[76:77], v[118:119]
	v_pk_mul_f32 v[120:121], v[78:79], v[120:121]
	v_pk_fma_f32 v[114:115], v[80:81], v[98:99], v[114:115]
	v_pk_fma_f32 v[116:117], v[82:83], v[100:101], v[116:117]
	v_pk_fma_f32 v[118:119], v[84:85], v[102:103], v[118:119]
	v_pk_fma_f32 v[120:121], v[86:87], v[104:105], v[120:121]
	v_pk_fma_f32 v[114:115], v[88:89], v[106:107], v[114:115]
	v_pk_fma_f32 v[116:117], v[90:91], v[108:109], v[116:117]
	v_pk_fma_f32 v[118:119], v[92:93], v[110:111], v[118:119]
	v_pk_fma_f32 v[120:121], v[94:95], v[112:113], v[120:121]
	v_cvt_pk_bf16_f32 v32, v114, v115
	v_cvt_pk_bf16_f32 v33, v116, v117
	v_cvt_pk_bf16_f32 v34, v118, v119
	v_cvt_pk_bf16_f32 v35, v120, v121
	global_store_dwordx4 v[124:125], v[32:35], off nt
	v_lshl_add_u64 v[124:125], v[126:127], 0, v[124:125]
	s_waitcnt vmcnt(15)
; DEV float lo_bf(unsigned u) { return __uint_as_float(u << 16); }
; DEV float hi_bf(unsigned u) { return __uint_as_float(u & 0xffff0000u); }
; DEV float sigmoidf_(float x) { return __builtin_amdgcn_rcpf(1.f + __expf(-x)); }
; DEV void shift_tile(const Params& p, int l, int tile) {
;     ...
; #pragma unroll
;   for (int i = 0; i < 16; ++i) {
;     const int row = rb + i;
;     const u32x4 pv = rows[i], cu = rows[i + 1], nx = rows[i + 2];
;     float y[8];
; #pragma unroll
;     for (int q = 0; q < 4; ++q) {
;       y[2 * q] = w0[2 * q] * lo_bf(pv[q]) + w1[2 * q] * lo_bf(cu[q]) + w2[2 * q] * lo_bf(nx[q]);
;       y[2 * q + 1] = w0[2 * q + 1] * hi_bf(pv[q]) + w1[2 * q + 1] * hi_bf(cu[q]) + w2[2 * q + 1] * hi_bf(nx[q]);
;     }
;     if (act == 1) {
; #pragma unroll
;       for (int j = 0; j < 8; ++j) y[j] = 1.f - 2.f * __builtin_amdgcn_rcpf(1.f + __expf(2.f * y[j]));
;     } else if (act == 2) {
; #pragma unroll
;       for (int j = 0; j < 8; ++j) y[j] = sigmoidf_(y[j]);
;     }
;     u32x4 o;
;     o[0] = pk2(y[0], y[1]); o[1] = pk2(y[2], y[3]); o[2] = pk2(y[4], y[5]); o[3] = pk2(y[6], y[7]);
;     if (col < 1536) *(u32x4*)(ZRS + (size_t)row * 1536 + col) = o;
	v_lshlrev_b32_e32 v114, 16, v44
	v_and_b32_e32 v115, 0xffff0000, v44
	v_lshlrev_b32_e32 v116, 16, v45
	v_and_b32_e32 v117, 0xffff0000, v45
	v_lshlrev_b32_e32 v118, 16, v46
	v_and_b32_e32 v119, 0xffff0000, v46
	v_lshlrev_b32_e32 v120, 16, v47
	v_and_b32_e32 v121, 0xffff0000, v47
	v_pk_mul_f32 v[98:99], v[72:73], v[98:99]
	v_pk_mul_f32 v[100:101], v[74:75], v[100:101]
	v_pk_mul_f32 v[102:103], v[76:77], v[102:103]
	v_pk_mul_f32 v[104:105], v[78:79], v[104:105]
	v_pk_fma_f32 v[98:99], v[80:81], v[106:107], v[98:99]
	v_pk_fma_f32 v[100:101], v[82:83], v[108:109], v[100:101]
	v_pk_fma_f32 v[102:103], v[84:85], v[110:111], v[102:103]
	v_pk_fma_f32 v[104:105], v[86:87], v[112:113], v[104:105]
	v_pk_fma_f32 v[98:99], v[88:89], v[114:115], v[98:99]
	v_pk_fma_f32 v[100:101], v[90:91], v[116:117], v[100:101]
	v_pk_fma_f32 v[102:103], v[92:93], v[118:119], v[102:103]
	v_pk_fma_f32 v[104:105], v[94:95], v[120:121], v[104:105]
	v_cvt_pk_bf16_f32 v36, v98, v99
	v_cvt_pk_bf16_f32 v37, v100, v101
	v_cvt_pk_bf16_f32 v38, v102, v103
	v_cvt_pk_bf16_f32 v39, v104, v105
	global_store_dwordx4 v[124:125], v[36:39], off nt
	v_lshl_add_u64 v[124:125], v[126:127], 0, v[124:125]
	s_waitcnt vmcnt(15)
	v_lshlrev_b32_e32 v98, 16, v48
	v_and_b32_e32 v99, 0xffff0000, v48
	v_lshlrev_b32_e32 v100, 16, v49
	v_and_b32_e32 v101, 0xffff0000, v49
	v_lshlrev_b32_e32 v102, 16, v50
	v_and_b32_e32 v103, 0xffff0000, v50
	v_lshlrev_b32_e32 v104, 16, v51
	v_and_b32_e32 v105, 0xffff0000, v51
	v_pk_mul_f32 v[106:107], v[72:73], v[106:107]
	v_pk_mul_f32 v[108:109], v[74:75], v[108:109]
	v_pk_mul_f32 v[110:111], v[76:77], v[110:111]
	v_pk_mul_f32 v[112:113], v[78:79], v[112:113]
	v_pk_fma_f32 v[106:107], v[80:81], v[114:115], v[106:107]
	v_pk_fma_f32 v[108:109], v[82:83], v[116:117], v[108:109]
	v_pk_fma_f32 v[110:111], v[84:85], v[118:119], v[110:111]
	v_pk_fma_f32 v[112:113], v[86:87], v[120:121], v[112:113]
	v_pk_fma_f32 v[106:107], v[88:89], v[98:99], v[106:107]
	v_pk_fma_f32 v[108:109], v[90:91], v[100:101], v[108:109]
	v_pk_fma_f32 v[110:111], v[92:93], v[102:103], v[110:111]
	v_pk_fma_f32 v[112:113], v[94:95], v[104:105], v[112:113]
	v_cvt_pk_bf16_f32 v40, v106, v107
	v_cvt_pk_bf16_f32 v41, v108, v109
	v_cvt_pk_bf16_f32 v42, v110, v111
	v_cvt_pk_bf16_f32 v43, v112, v113
	global_store_dwordx4 v[124:125], v[40:43], off nt
	v_lshl_add_u64 v[124:125], v[126:127], 0, v[124:125]
	s_waitcnt vmcnt(15)
	v_lshlrev_b32_e32 v106, 16, v52
	v_and_b32_e32 v107, 0xffff0000, v52
	v_lshlrev_b32_e32 v108, 16, v53
	v_and_b32_e32 v109, 0xffff0000, v53
	v_lshlrev_b32_e32 v110, 16, v54
	v_and_b32_e32 v111, 0xffff0000, v54
	v_lshlrev_b32_e32 v112, 16, v55
	v_and_b32_e32 v113, 0xffff0000, v55
	v_pk_mul_f32 v[114:115], v[72:73], v[114:115]
	v_pk_mul_f32 v[116:117], v[74:75], v[116:117]
	v_pk_mul_f32 v[118:119], v[76:77], v[118:119]
	v_pk_mul_f32 v[120:121], v[78:79], v[120:121]
	v_pk_fma_f32 v[114:115], v[80:81], v[98:99], v[114:115]
	v_pk_fma_f32 v[116:117], v[82:83], v[100:101], v[116:117]
	v_pk_fma_f32 v[118:119], v[84:85], v[102:103], v[118:119]
	v_pk_fma_f32 v[120:121], v[86:87], v[104:105], v[120:121]
	v_pk_fma_f32 v[114:115], v[88:89], v[106:107], v[114:115]
	v_pk_fma_f32 v[116:117], v[90:91], v[108:109], v[116:117]
	v_pk_fma_f32 v[118:119], v[92:93], v[110:111], v[118:119]
	v_pk_fma_f32 v[120:121], v[94:95], v[112:113], v[120:121]
	v_cvt_pk_bf16_f32 v44, v114, v115
	v_cvt_pk_bf16_f32 v45, v116, v117
	v_cvt_pk_bf16_f32 v46, v118, v119
	v_cvt_pk_bf16_f32 v47, v120, v121
	global_store_dwordx4 v[124:125], v[44:47], off nt
	v_lshl_add_u64 v[124:125], v[126:127], 0, v[124:125]
	s_waitcnt vmcnt(15)
	v_lshlrev_b32_e32 v114, 16, v56
	v_and_b32_e32 v115, 0xffff0000, v56
	v_lshlrev_b32_e32 v116, 16, v57
	v_and_b32_e32 v117, 0xffff0000, v57
	v_lshlrev_b32_e32 v118, 16, v58
	v_and_b32_e32 v119, 0xffff0000, v58
	v_lshlrev_b32_e32 v120, 16, v59
	v_and_b32_e32 v121, 0xffff0000, v59
	v_pk_mul_f32 v[98:99], v[72:73], v[98:99]
	v_pk_mul_f32 v[100:101], v[74:75], v[100:101]
	v_pk_mul_f32 v[102:103], v[76:77], v[102:103]
	v_pk_mul_f32 v[104:105], v[78:79], v[104:105]
	v_pk_fma_f32 v[98:99], v[80:81], v[106:107], v[98:99]
	v_pk_fma_f32 v[100:101], v[82:83], v[108:109], v[100:101]
	v_pk_fma_f32 v[102:103], v[84:85], v[110:111], v[102:103]
	v_pk_fma_f32 v[104:105], v[86:87], v[112:113], v[104:105]
	v_pk_fma_f32 v[98:99], v[88:89], v[114:115], v[98:99]
	v_pk_fma_f32 v[100:101], v[90:91], v[116:117], v[100:101]
	v_pk_fma_f32 v[102:103], v[92:93], v[118:119], v[102:103]
	v_pk_fma_f32 v[104:105], v[94:95], v[120:121], v[104:105]
	v_cvt_pk_bf16_f32 v48, v98, v99
	v_cvt_pk_bf16_f32 v49, v100, v101
	v_cvt_pk_bf16_f32 v50, v102, v103
	v_cvt_pk_bf16_f32 v51, v104, v105
	global_store_dwordx4 v[124:125], v[48:51], off nt
	v_lshl_add_u64 v[124:125], v[126:127], 0, v[124:125]
	s_waitcnt vmcnt(15)
	v_lshlrev_b32_e32 v98, 16, v60
	v_and_b32_e32 v99, 0xffff0000, v60
	v_lshlrev_b32_e32 v100, 16, v61
	v_and_b32_e32 v101, 0xffff0000, v61
	v_lshlrev_b32_e32 v102, 16, v62
	v_and_b32_e32 v103, 0xffff0000, v62
	v_lshlrev_b32_e32 v104, 16, v63
	v_and_b32_e32 v105, 0xffff0000, v63
	v_pk_mul_f32 v[106:107], v[72:73], v[106:107]
	v_pk_mul_f32 v[108:109], v[74:75], v[108:109]
	v_pk_mul_f32 v[110:111], v[76:77], v[110:111]
	v_pk_mul_f32 v[112:113], v[78:79], v[112:113]
	v_pk_fma_f32 v[106:107], v[80:81], v[114:115], v[106:107]
	v_pk_fma_f32 v[108:109], v[82:83], v[116:117], v[108:109]
	v_pk_fma_f32 v[110:111], v[84:85], v[118:119], v[110:111]
	v_pk_fma_f32 v[112:113], v[86:87], v[120:121], v[112:113]
	v_pk_fma_f32 v[106:107], v[88:89], v[98:99], v[106:107]
	v_pk_fma_f32 v[108:109], v[90:91], v[100:101], v[108:109]
	v_pk_fma_f32 v[110:111], v[92:93], v[102:103], v[110:111]
	v_pk_fma_f32 v[112:113], v[94:95], v[104:105], v[112:113]
	v_cvt_pk_bf16_f32 v52, v106, v107
	v_cvt_pk_bf16_f32 v53, v108, v109
	v_cvt_pk_bf16_f32 v54, v110, v111
	v_cvt_pk_bf16_f32 v55, v112, v113
	global_store_dwordx4 v[124:125], v[52:55], off nt
	v_lshl_add_u64 v[124:125], v[126:127], 0, v[124:125]
	s_waitcnt vmcnt(15)
; DEV float lo_bf(unsigned u) { return __uint_as_float(u << 16); }
; DEV float hi_bf(unsigned u) { return __uint_as_float(u & 0xffff0000u); }
; DEV float sigmoidf_(float x) { return __builtin_amdgcn_rcpf(1.f + __expf(-x)); }
; DEV void shift_tile(const Params& p, int l, int tile) {
;     ...
; #pragma unroll
;   for (int i = 0; i < 16; ++i) {
;     const int row = rb + i;
;     const u32x4 pv = rows[i], cu = rows[i + 1], nx = rows[i + 2];
;     float y[8];
; #pragma unroll
;     for (int q = 0; q < 4; ++q) {
;       y[2 * q] = w0[2 * q] * lo_bf(pv[q]) + w1[2 * q] * lo_bf(cu[q]) + w2[2 * q] * lo_bf(nx[q]);
;       y[2 * q + 1] = w0[2 * q + 1] * hi_bf(pv[q]) + w1[2 * q + 1] * hi_bf(cu[q]) + w2[2 * q + 1] * hi_bf(nx[q]);
;     }
;     if (act == 1) {
; #pragma unroll
;       for (int j = 0; j < 8; ++j) y[j] = 1.f - 2.f * __builtin_amdgcn_rcpf(1.f + __expf(2.f * y[j]));
;     } else if (act == 2) {
; #pragma unroll
;       for (int j = 0; j < 8; ++j) y[j] = sigmoidf_(y[j]);
;     }
;     u32x4 o;
;     o[0] = pk2(y[0], y[1]); o[1] = pk2(y[2], y[3]); o[2] = pk2(y[4], y[5]); o[3] = pk2(y[6], y[7]);
;     if (col < 1536) *(u32x4*)(ZRS + (size_t)row * 1536 + col) = o;
	v_lshlrev_b32_e32 v106, 16, v64
	v_and_b32_e32 v107, 0xffff0000, v64
	v_lshlrev_b32_e32 v108, 16, v65
	v_and_b32_e32 v109, 0xffff0000, v65
	v_lshlrev_b32_e32 v110, 16, v66
	v_and_b32_e32 v111, 0xffff0000, v66
	v_lshlrev_b32_e32 v112, 16, v67
	v_and_b32_e32 v113, 0xffff0000, v67
	v_pk_mul_f32 v[114:115], v[72:73], v[114:115]
	v_pk_mul_f32 v[116:117], v[74:75], v[116:117]
	v_pk_mul_f32 v[118:119], v[76:77], v[118:119]
	v_pk_mul_f32 v[120:121], v[78:79], v[120:121]
	v_pk_fma_f32 v[114:115], v[80:81], v[98:99], v[114:115]
	v_pk_fma_f32 v[116:117], v[82:83], v[100:101], v[116:117]
	v_pk_fma_f32 v[118:119], v[84:85], v[102:103], v[118:119]
	v_pk_fma_f32 v[120:121], v[86:87], v[104:105], v[120:121]
	v_pk_fma_f32 v[114:115], v[88:89], v[106:107], v[114:115]
	v_pk_fma_f32 v[116:117], v[90:91], v[108:109], v[116:117]
	v_pk_fma_f32 v[118:119], v[92:93], v[110:111], v[118:119]
	v_pk_fma_f32 v[120:121], v[94:95], v[112:113], v[120:121]
	v_cvt_pk_bf16_f32 v56, v114, v115
	v_cvt_pk_bf16_f32 v57, v116, v117
	v_cvt_pk_bf16_f32 v58, v118, v119
	v_cvt_pk_bf16_f32 v59, v120, v121
	global_store_dwordx4 v[124:125], v[56:59], off nt
	v_lshl_add_u64 v[124:125], v[126:127], 0, v[124:125]
	s_waitcnt vmcnt(15)
	v_lshlrev_b32_e32 v114, 16, v68
	v_and_b32_e32 v115, 0xffff0000, v68
	v_lshlrev_b32_e32 v116, 16, v69
	v_and_b32_e32 v117, 0xffff0000, v69
	v_lshlrev_b32_e32 v118, 16, v70
	v_and_b32_e32 v119, 0xffff0000, v70
	v_lshlrev_b32_e32 v120, 16, v71
	v_and_b32_e32 v121, 0xffff0000, v71
	v_pk_mul_f32 v[98:99], v[72:73], v[98:99]
	v_pk_mul_f32 v[100:101], v[74:75], v[100:101]
	v_pk_mul_f32 v[102:103], v[76:77], v[102:103]
	v_pk_mul_f32 v[104:105], v[78:79], v[104:105]
	v_pk_fma_f32 v[98:99], v[80:81], v[106:107], v[98:99]
	v_pk_fma_f32 v[100:101], v[82:83], v[108:109], v[100:101]
	v_pk_fma_f32 v[102:103], v[84:85], v[110:111], v[102:103]
	v_pk_fma_f32 v[104:105], v[86:87], v[112:113], v[104:105]
	v_pk_fma_f32 v[98:99], v[88:89], v[114:115], v[98:99]
	v_pk_fma_f32 v[100:101], v[90:91], v[116:117], v[100:101]
	v_pk_fma_f32 v[102:103], v[92:93], v[118:119], v[102:103]
	v_pk_fma_f32 v[104:105], v[94:95], v[120:121], v[104:105]
	v_cvt_pk_bf16_f32 v60, v98, v99
	v_cvt_pk_bf16_f32 v61, v100, v101
	v_cvt_pk_bf16_f32 v62, v102, v103
	v_cvt_pk_bf16_f32 v63, v104, v105
	global_store_dwordx4 v[124:125], v[60:63], off nt
	s_branch .Lsh_end
.Lsh_full:
	s_waitcnt vmcnt(15)
	v_lshlrev_b32_e32 v98, 16, v0
	v_and_b32_e32 v99, 0xffff0000, v0
	v_lshlrev_b32_e32 v100, 16, v1
	v_and_b32_e32 v101, 0xffff0000, v1
	v_lshlrev_b32_e32 v102, 16, v2
	v_and_b32_e32 v103, 0xffff0000, v2
	v_lshlrev_b32_e32 v104, 16, v3
	v_and_b32_e32 v105, 0xffff0000, v3
	v_lshlrev_b32_e32 v106, 16, v4
	v_and_b32_e32 v107, 0xffff0000, v4
	v_lshlrev_b32_e32 v108, 16, v5
	v_and_b32_e32 v109, 0xffff0000, v5
	v_lshlrev_b32_e32 v110, 16, v6
	v_and_b32_e32 v111, 0xffff0000, v6
	v_lshlrev_b32_e32 v112, 16, v7
	v_and_b32_e32 v113, 0xffff0000, v7
	v_lshlrev_b32_e32 v114, 16, v8
	v_and_b32_e32 v115, 0xffff0000, v8
	v_lshlrev_b32_e32 v116, 16, v9
	v_and_b32_e32 v117, 0xffff0000, v9
	v_lshlrev_b32_e32 v118, 16, v10
	v_and_b32_e32 v119, 0xffff0000, v10
	v_lshlrev_b32_e32 v120, 16, v11
	v_and_b32_e32 v121, 0xffff0000, v11
	v_pk_mul_f32 v[98:99], v[72:73], v[98:99]
	v_pk_mul_f32 v[100:101], v[74:75], v[100:101]
	v_pk_mul_f32 v[102:103], v[76:77], v[102:103]
	v_pk_mul_f32 v[104:105], v[78:79], v[104:105]
	v_pk_fma_f32 v[98:99], v[80:81], v[106:107], v[98:99]
	v_pk_fma_f32 v[100:101], v[82:83], v[108:109], v[100:101]
	v_pk_fma_f32 v[102:103], v[84:85], v[110:111], v[102:103]
	v_pk_fma_f32 v[104:105], v[86:87], v[112:113], v[104:105]
	v_pk_fma_f32 v[98:99], v[88:89], v[114:115], v[98:99]
	v_pk_fma_f32 v[100:101], v[90:91], v[116:117], v[100:101]
	v_pk_fma_f32 v[102:103], v[92:93], v[118:119], v[102:103]
	v_pk_fma_f32 v[104:105], v[94:95], v[120:121], v[104:105]
	v_pk_mul_f32 v[98:99], v[98:99], v[130:131]
	v_pk_mul_f32 v[100:101], v[100:101], v[130:131]
	v_pk_mul_f32 v[102:103], v[102:103], v[130:131]
	v_pk_mul_f32 v[104:105], v[104:105], v[130:131]
	v_exp_f32_e32 v98, v98
	v_exp_f32_e32 v99, v99
	v_exp_f32_e32 v100, v100
	v_exp_f32_e32 v101, v101
	v_exp_f32_e32 v102, v102
	v_exp_f32_e32 v103, v103
	v_exp_f32_e32 v104, v104
	v_exp_f32_e32 v105, v105
	v_pk_add_f32 v[98:99], v[98:99], 1.0 op_sel_hi:[1,0]
	v_pk_add_f32 v[100:101], v[100:101], 1.0 op_sel_hi:[1,0]
	v_pk_add_f32 v[102:103], v[102:103], 1.0 op_sel_hi:[1,0]
	v_pk_add_f32 v[104:105], v[104:105], 1.0 op_sel_hi:[1,0]
	v_rcp_f32_e32 v98, v98
	v_rcp_f32_e32 v99, v99
	v_rcp_f32_e32 v100, v100
	v_rcp_f32_e32 v101, v101
	v_rcp_f32_e32 v102, v102
	v_rcp_f32_e32 v103, v103
	v_rcp_f32_e32 v104, v104
	v_rcp_f32_e32 v105, v105
	v_pk_fma_f32 v[98:99], v[98:99], v[132:133], v[134:135]
	v_pk_fma_f32 v[100:101], v[100:101], v[132:133], v[134:135]
	v_pk_fma_f32 v[102:103], v[102:103], v[132:133], v[134:135]
	v_pk_fma_f32 v[104:105], v[104:105], v[132:133], v[134:135]
	v_cvt_pk_bf16_f32 v0, v98, v99
	v_cvt_pk_bf16_f32 v1, v100, v101
	v_cvt_pk_bf16_f32 v2, v102, v103
	v_cvt_pk_bf16_f32 v3, v104, v105
	global_store_dwordx4 v[124:125], v[0:3], off nt
	v_lshl_add_u64 v[124:125], v[126:127], 0, v[124:125]
	s_waitcnt vmcnt(15)
; DEV float lo_bf(unsigned u) { return __uint_as_float(u << 16); }
; DEV float hi_bf(unsigned u) { return __uint_as_float(u & 0xffff0000u); }
; DEV float sigmoidf_(float x) { return __builtin_amdgcn_rcpf(1.f + __expf(-x)); }
; DEV void shift_tile(const Params& p, int l, int tile) {
;     ...
; #pragma unroll
;   for (int i = 0; i < 16; ++i) {
;     const int row = rb + i;
;     const u32x4 pv = rows[i], cu = rows[i + 1], nx = rows[i + 2];
;     float y[8];
; #pragma unroll
;     for (int q = 0; q < 4; ++q) {
;       y[2 * q] = w0[2 * q] * lo_bf(pv[q]) + w1[2 * q] * lo_bf(cu[q]) + w2[2 * q] * lo_bf(nx[q]);
;       y[2 * q + 1] = w0[2 * q + 1] * hi_bf(pv[q]) + w1[2 * q + 1] * hi_bf(cu[q]) + w2[2 * q + 1] * hi_bf(nx[q]);
;     }
;     if (act == 1) {
; #pragma unroll
;       for (int j = 0; j < 8; ++j) y[j] = 1.f - 2.f * __builtin_amdgcn_rcpf(1.f + __expf(2.f * y[j]));
;     } else if (act == 2) {
; #pragma unroll
;       for (int j = 0; j < 8; ++j) y[j] = sigmoidf_(y[j]);
;     }
;     u32x4 o;
;     o[0] = pk2(y[0], y[1]); o[1] = pk2(y[2], y[3]); o[2] = pk2(y[4], y[5]); o[3] = pk2(y[6], y[7]);
;     if (col < 1536) *(u32x4*)(ZRS + (size_t)row * 1536 + col) = o;
	v_lshlrev_b32_e32 v98, 16, v12
	v_and_b32_e32 v99, 0xffff0000, v12
	v_lshlrev_b32_e32 v100, 16, v13
	v_and_b32_e32 v101, 0xffff0000, v13
	v_lshlrev_b32_e32 v102, 16, v14
	v_and_b32_e32 v103, 0xffff0000, v14
	v_lshlrev_b32_e32 v104, 16, v15
	v_and_b32_e32 v105, 0xffff0000, v15
	v_pk_mul_f32 v[106:107], v[72:73], v[106:107]
	v_pk_mul_f32 v[108:109], v[74:75], v[108:109]
	v_pk_mul_f32 v[110:111], v[76:77], v[110:111]
	v_pk_mul_f32 v[112:113], v[78:79], v[112:113]
	v_pk_fma_f32 v[106:107], v[80:81], v[114:115], v[106:107]
	v_pk_fma_f32 v[108:109], v[82:83], v[116:117], v[108:109]
	v_pk_fma_f32 v[110:111], v[84:85], v[118:119], v[110:111]
	v_pk_fma_f32 v[112:113], v[86:87], v[120:121], v[112:113]
	v_pk_fma_f32 v[106:107], v[88:89], v[98:99], v[106:107]
	v_pk_fma_f32 v[108:109], v[90:91], v[100:101], v[108:109]
	v_pk_fma_f32 v[110:111], v[92:93], v[102:103], v[110:111]
	v_pk_fma_f32 v[112:113], v[94:95], v[104:105], v[112:113]
	v_pk_mul_f32 v[106:107], v[106:107], v[130:131]
	v_pk_mul_f32 v[108:109], v[108:109], v[130:131]
	v_pk_mul_f32 v[110:111], v[110:111], v[130:131]
	v_pk_mul_f32 v[112:113], v[112:113], v[130:131]
	v_exp_f32_e32 v106, v106
	v_exp_f32_e32 v107, v107
	v_exp_f32_e32 v108, v108
	v_exp_f32_e32 v109, v109
	v_exp_f32_e32 v110, v110
	v_exp_f32_e32 v111, v111
	v_exp_f32_e32 v112, v112
	v_exp_f32_e32 v113, v113
	v_pk_add_f32 v[106:107], v[106:107], 1.0 op_sel_hi:[1,0]
	v_pk_add_f32 v[108:109], v[108:109], 1.0 op_sel_hi:[1,0]
	v_pk_add_f32 v[110:111], v[110:111], 1.0 op_sel_hi:[1,0]
	v_pk_add_f32 v[112:113], v[112:113], 1.0 op_sel_hi:[1,0]
	v_rcp_f32_e32 v106, v106
	v_rcp_f32_e32 v107, v107
	v_rcp_f32_e32 v108, v108
	v_rcp_f32_e32 v109, v109
	v_rcp_f32_e32 v110, v110
	v_rcp_f32_e32 v111, v111
	v_rcp_f32_e32 v112, v112
	v_rcp_f32_e32 v113, v113
	v_pk_fma_f32 v[106:107], v[106:107], v[132:133], v[134:135]
	v_pk_fma_f32 v[108:109], v[108:109], v[132:133], v[134:135]
	v_pk_fma_f32 v[110:111], v[110:111], v[132:133], v[134:135]
	v_pk_fma_f32 v[112:113], v[112:113], v[132:133], v[134:135]
	v_cvt_pk_bf16_f32 v4, v106, v107
	v_cvt_pk_bf16_f32 v5, v108, v109
	v_cvt_pk_bf16_f32 v6, v110, v111
	v_cvt_pk_bf16_f32 v7, v112, v113
	global_store_dwordx4 v[124:125], v[4:7], off nt
	v_lshl_add_u64 v[124:125], v[126:127], 0, v[124:125]
	s_waitcnt vmcnt(15)
	v_lshlrev_b32_e32 v106, 16, v16
	v_and_b32_e32 v107, 0xffff0000, v16
	v_lshlrev_b32_e32 v108, 16, v17
	v_and_b32_e32 v109, 0xffff0000, v17
	v_lshlrev_b32_e32 v110, 16, v18
	v_and_b32_e32 v111, 0xffff0000, v18
	v_lshlrev_b32_e32 v112, 16, v19
	v_and_b32_e32 v113, 0xffff0000, v19
	v_pk_mul_f32 v[114:115], v[72:73], v[114:115]
	v_pk_mul_f32 v[116:117], v[74:75], v[116:117]
	v_pk_mul_f32 v[118:119], v[76:77], v[118:119]
	v_pk_mul_f32 v[120:121], v[78:79], v[120:121]
	v_pk_fma_f32 v[114:115], v[80:81], v[98:99], v[114:115]
	v_pk_fma_f32 v[116:117], v[82:83], v[100:101], v[116:117]
	v_pk_fma_f32 v[118:119], v[84:85], v[102:103], v[118:119]
	v_pk_fma_f32 v[120:121], v[86:87], v[104:105], v[120:121]
	v_pk_fma_f32 v[114:115], v[88:89], v[106:107], v[114:115]
	v_pk_fma_f32 v[116:117], v[90:91], v[108:109], v[116:117]
	v_pk_fma_f32 v[118:119], v[92:93], v[110:111], v[118:119]
	v_pk_fma_f32 v[120:121], v[94:95], v[112:113], v[120:121]
	v_pk_mul_f32 v[114:115], v[114:115], v[130:131]
	v_pk_mul_f32 v[116:117], v[116:117], v[130:131]
	v_pk_mul_f32 v[118:119], v[118:119], v[130:131]
	v_pk_mul_f32 v[120:121], v[120:121], v[130:131]
	v_exp_f32_e32 v114, v114
	v_exp_f32_e32 v115, v115
	v_exp_f32_e32 v116, v116
	v_exp_f32_e32 v117, v117
	v_exp_f32_e32 v118, v118
	v_exp_f32_e32 v119, v119
	v_exp_f32_e32 v120, v120
	v_exp_f32_e32 v121, v121
	v_pk_add_f32 v[114:115], v[114:115], 1.0 op_sel_hi:[1,0]
	v_pk_add_f32 v[116:117], v[116:117], 1.0 op_sel_hi:[1,0]
	v_pk_add_f32 v[118:119], v[118:119], 1.0 op_sel_hi:[1,0]
	v_pk_add_f32 v[120:121], v[120:121], 1.0 op_sel_hi:[1,0]
	v_rcp_f32_e32 v114, v114
	v_rcp_f32_e32 v115, v115
	v_rcp_f32_e32 v116, v116
	v_rcp_f32_e32 v117, v117
	v_rcp_f32_e32 v118, v118
	v_rcp_f32_e32 v119, v119
	v_rcp_f32_e32 v120, v120
	v_rcp_f32_e32 v121, v121
	v_pk_fma_f32 v[114:115], v[114:115], v[132:133], v[134:135]
	v_pk_fma_f32 v[116:117], v[116:117], v[132:133], v[134:135]
	v_pk_fma_f32 v[118:119], v[118:119], v[132:133], v[134:135]
	v_pk_fma_f32 v[120:121], v[120:121], v[132:133], v[134:135]
	v_cvt_pk_bf16_f32 v8, v114, v115
	v_cvt_pk_bf16_f32 v9, v116, v117
	v_cvt_pk_bf16_f32 v10, v118, v119
	v_cvt_pk_bf16_f32 v11, v120, v121
	global_store_dwordx4 v[124:125], v[8:11], off nt
	v_lshl_add_u64 v[124:125], v[126:127], 0, v[124:125]
	s_waitcnt vmcnt(15)
; DEV float lo_bf(unsigned u) { return __uint_as_float(u << 16); }
; DEV float hi_bf(unsigned u) { return __uint_as_float(u & 0xffff0000u); }
; DEV float sigmoidf_(float x) { return __builtin_amdgcn_rcpf(1.f + __expf(-x)); }
; DEV void shift_tile(const Params& p, int l, int tile) {
;     ...
; #pragma unroll
;   for (int i = 0; i < 16; ++i) {
;     const int row = rb + i;
;     const u32x4 pv = rows[i], cu = rows[i + 1], nx = rows[i + 2];
;     float y[8];
; #pragma unroll
;     for (int q = 0; q < 4; ++q) {
;       y[2 * q] = w0[2 * q] * lo_bf(pv[q]) + w1[2 * q] * lo_bf(cu[q]) + w2[2 * q] * lo_bf(nx[q]);
;       y[2 * q + 1] = w0[2 * q + 1] * hi_bf(pv[q]) + w1[2 * q + 1] * hi_bf(cu[q]) + w2[2 * q + 1] * hi_bf(nx[q]);
;     }
;     if (act == 1) {
; #pragma unroll
;       for (int j = 0; j < 8; ++j) y[j] = 1.f - 2.f * __builtin_amdgcn_rcpf(1.f + __expf(2.f * y[j]));
;     } else if (act == 2) {
; #pragma unroll
;       for (int j = 0; j < 8; ++j) y[j] = sigmoidf_(y[j]);
;     }
;     u32x4 o;
;     o[0] = pk2(y[0], y[1]); o[1] = pk2(y[2], y[3]); o[2] = pk2(y[4], y[5]); o[3] = pk2(y[6], y[7]);
;     if (col < 1536) *(u32x4*)(ZRS + (size_t)row * 1536 + col) = o;
	v_lshlrev_b32_e32 v114, 16, v20
	v_and_b32_e32 v115, 0xffff0000, v20
	v_lshlrev_b32_e32 v116, 16, v21
	v_and_b32_e32 v117, 0xffff0000, v21
	v_lshlrev_b32_e32 v118, 16, v22
	v_and_b32_e32 v119, 0xffff0000, v22
	v_lshlrev_b32_e32 v120, 16, v23
	v_and_b32_e32 v121, 0xffff0000, v23
	v_pk_mul_f32 v[98:99], v[72:73], v[98:99]
	v_pk_mul_f32 v[100:101], v[74:75], v[100:101]
	v_pk_mul_f32 v[102:103], v[76:77], v[102:103]
	v_pk_mul_f32 v[104:105], v[78:79], v[104:105]
	v_pk_fma_f32 v[98:99], v[80:81], v[106:107], v[98:99]
	v_pk_fma_f32 v[100:101], v[82:83], v[108:109], v[100:101]
	v_pk_fma_f32 v[102:103], v[84:85], v[110:111], v[102:103]
	v_pk_fma_f32 v[104:105], v[86:87], v[112:113], v[104:105]
	v_pk_fma_f32 v[98:99], v[88:89], v[114:115], v[98:99]
	v_pk_fma_f32 v[100:101], v[90:91], v[116:117], v[100:101]
	v_pk_fma_f32 v[102:103], v[92:93], v[118:119], v[102:103]
	v_pk_fma_f32 v[104:105], v[94:95], v[120:121], v[104:105]
	v_pk_mul_f32 v[98:99], v[98:99], v[130:131]
	v_pk_mul_f32 v[100:101], v[100:101], v[130:131]
	v_pk_mul_f32 v[102:103], v[102:103], v[130:131]
	v_pk_mul_f32 v[104:105], v[104:105], v[130:131]
	v_exp_f32_e32 v98, v98
	v_exp_f32_e32 v99, v99
	v_exp_f32_e32 v100, v100
	v_exp_f32_e32 v101, v101
	v_exp_f32_e32 v102, v102
	v_exp_f32_e32 v103, v103
	v_exp_f32_e32 v104, v104
	v_exp_f32_e32 v105, v105
	v_pk_add_f32 v[98:99], v[98:99], 1.0 op_sel_hi:[1,0]
	v_pk_add_f32 v[100:101], v[100:101], 1.0 op_sel_hi:[1,0]
	v_pk_add_f32 v[102:103], v[102:103], 1.0 op_sel_hi:[1,0]
	v_pk_add_f32 v[104:105], v[104:105], 1.0 op_sel_hi:[1,0]
	v_rcp_f32_e32 v98, v98
	v_rcp_f32_e32 v99, v99
	v_rcp_f32_e32 v100, v100
	v_rcp_f32_e32 v101, v101
	v_rcp_f32_e32 v102, v102
	v_rcp_f32_e32 v103, v103
	v_rcp_f32_e32 v104, v104
	v_rcp_f32_e32 v105, v105
	v_pk_fma_f32 v[98:99], v[98:99], v[132:133], v[134:135]
	v_pk_fma_f32 v[100:101], v[100:101], v[132:133], v[134:135]
	v_pk_fma_f32 v[102:103], v[102:103], v[132:133], v[134:135]
	v_pk_fma_f32 v[104:105], v[104:105], v[132:133], v[134:135]
	v_cvt_pk_bf16_f32 v12, v98, v99
	v_cvt_pk_bf16_f32 v13, v100, v101
	v_cvt_pk_bf16_f32 v14, v102, v103
	v_cvt_pk_bf16_f32 v15, v104, v105
	global_store_dwordx4 v[124:125], v[12:15], off nt
	v_lshl_add_u64 v[124:125], v[126:127], 0, v[124:125]
	s_waitcnt vmcnt(15)
	v_lshlrev_b32_e32 v98, 16, v24
	v_and_b32_e32 v99, 0xffff0000, v24
	v_lshlrev_b32_e32 v100, 16, v25
	v_and_b32_e32 v101, 0xffff0000, v25
	v_lshlrev_b32_e32 v102, 16, v26
	v_and_b32_e32 v103, 0xffff0000, v26
	v_lshlrev_b32_e32 v104, 16, v27
	v_and_b32_e32 v105, 0xffff0000, v27
	v_pk_mul_f32 v[106:107], v[72:73], v[106:107]
	v_pk_mul_f32 v[108:109], v[74:75], v[108:109]
	v_pk_mul_f32 v[110:111], v[76:77], v[110:111]
	v_pk_mul_f32 v[112:113], v[78:79], v[112:113]
	v_pk_fma_f32 v[106:107], v[80:81], v[114:115], v[106:107]
	v_pk_fma_f32 v[108:109], v[82:83], v[116:117], v[108:109]
	v_pk_fma_f32 v[110:111], v[84:85], v[118:119], v[110:111]
	v_pk_fma_f32 v[112:113], v[86:87], v[120:121], v[112:113]
	v_pk_fma_f32 v[106:107], v[88:89], v[98:99], v[106:107]
	v_pk_fma_f32 v[108:109], v[90:91], v[100:101], v[108:109]
	v_pk_fma_f32 v[110:111], v[92:93], v[102:103], v[110:111]
	v_pk_fma_f32 v[112:113], v[94:95], v[104:105], v[112:113]
	v_pk_mul_f32 v[106:107], v[106:107], v[130:131]
	v_pk_mul_f32 v[108:109], v[108:109], v[130:131]
	v_pk_mul_f32 v[110:111], v[110:111], v[130:131]
	v_pk_mul_f32 v[112:113], v[112:113], v[130:131]
	v_exp_f32_e32 v106, v106
	v_exp_f32_e32 v107, v107
	v_exp_f32_e32 v108, v108
	v_exp_f32_e32 v109, v109
	v_exp_f32_e32 v110, v110
	v_exp_f32_e32 v111, v111
	v_exp_f32_e32 v112, v112
	v_exp_f32_e32 v113, v113
	v_pk_add_f32 v[106:107], v[106:107], 1.0 op_sel_hi:[1,0]
	v_pk_add_f32 v[108:109], v[108:109], 1.0 op_sel_hi:[1,0]
	v_pk_add_f32 v[110:111], v[110:111], 1.0 op_sel_hi:[1,0]
	v_pk_add_f32 v[112:113], v[112:113], 1.0 op_sel_hi:[1,0]
	v_rcp_f32_e32 v106, v106
	v_rcp_f32_e32 v107, v107
	v_rcp_f32_e32 v108, v108
	v_rcp_f32_e32 v109, v109
	v_rcp_f32_e32 v110, v110
	v_rcp_f32_e32 v111, v111
	v_rcp_f32_e32 v112, v112
	v_rcp_f32_e32 v113, v113
	v_pk_fma_f32 v[106:107], v[106:107], v[132:133], v[134:135]
	v_pk_fma_f32 v[108:109], v[108:109], v[132:133], v[134:135]
	v_pk_fma_f32 v[110:111], v[110:111], v[132:133], v[134:135]
	v_pk_fma_f32 v[112:113], v[112:113], v[132:133], v[134:135]
	v_cvt_pk_bf16_f32 v16, v106, v107
	v_cvt_pk_bf16_f32 v17, v108, v109
	v_cvt_pk_bf16_f32 v18, v110, v111
	v_cvt_pk_bf16_f32 v19, v112, v113
	global_store_dwordx4 v[124:125], v[16:19], off nt
	v_lshl_add_u64 v[124:125], v[126:127], 0, v[124:125]
	s_waitcnt vmcnt(15)
; DEV float lo_bf(unsigned u) { return __uint_as_float(u << 16); }
; DEV float hi_bf(unsigned u) { return __uint_as_float(u & 0xffff0000u); }
; DEV float sigmoidf_(float x) { return __builtin_amdgcn_rcpf(1.f + __expf(-x)); }
; DEV void shift_tile(const Params& p, int l, int tile) {
;     ...
; #pragma unroll
;   for (int i = 0; i < 16; ++i) {
;     const int row = rb + i;
;     const u32x4 pv = rows[i], cu = rows[i + 1], nx = rows[i + 2];
;     float y[8];
; #pragma unroll
;     for (int q = 0; q < 4; ++q) {
;       y[2 * q] = w0[2 * q] * lo_bf(pv[q]) + w1[2 * q] * lo_bf(cu[q]) + w2[2 * q] * lo_bf(nx[q]);
;       y[2 * q + 1] = w0[2 * q + 1] * hi_bf(pv[q]) + w1[2 * q + 1] * hi_bf(cu[q]) + w2[2 * q + 1] * hi_bf(nx[q]);
;     }
;     if (act == 1) {
; #pragma unroll
;       for (int j = 0; j < 8; ++j) y[j] = 1.f - 2.f * __builtin_amdgcn_rcpf(1.f + __expf(2.f * y[j]));
;     } else if (act == 2) {
; #pragma unroll
;       for (int j = 0; j < 8; ++j) y[j] = sigmoidf_(y[j]);
;     }
;     u32x4 o;
;     o[0] = pk2(y[0], y[1]); o[1] = pk2(y[2], y[3]); o[2] = pk2(y[4], y[5]); o[3] = pk2(y[6], y[7]);
;     if (col < 1536) *(u32x4*)(ZRS + (size_t)row * 1536 + col) = o;
	v_lshlrev_b32_e32 v106, 16, v28
	v_and_b32_e32 v107, 0xffff0000, v28
	v_lshlrev_b32_e32 v108, 16, v29
	v_and_b32_e32 v109, 0xffff0000, v29
	v_lshlrev_b32_e32 v110, 16, v30
	v_and_b32_e32 v111, 0xffff0000, v30
	v_lshlrev_b32_e32 v112, 16, v31
	v_and_b32_e32 v113, 0xffff0000, v31
	v_pk_mul_f32 v[114:115], v[72:73], v[114:115]
	v_pk_mul_f32 v[116:117], v[74:75], v[116:117]
	v_pk_mul_f32 v[118:119], v[76:77], v[118:119]
	v_pk_mul_f32 v[120:121], v[78:79], v[120:121]
	v_pk_fma_f32 v[114:115], v[80:81], v[98:99], v[114:115]
	v_pk_fma_f32 v[116:117], v[82:83], v[100:101], v[116:117]
	v_pk_fma_f32 v[118:119], v[84:85], v[102:103], v[118:119]
	v_pk_fma_f32 v[120:121], v[86:87], v[104:105], v[120:121]
	v_pk_fma_f32 v[114:115], v[88:89], v[106:107], v[114:115]
	v_pk_fma_f32 v[116:117], v[90:91], v[108:109], v[116:117]
	v_pk_fma_f32 v[118:119], v[92:93], v[110:111], v[118:119]
	v_pk_fma_f32 v[120:121], v[94:95], v[112:113], v[120:121]
	v_pk_mul_f32 v[114:115], v[114:115], v[130:131]
	v_pk_mul_f32 v[116:117], v[116:117], v[130:131]
	v_pk_mul_f32 v[118:119], v[118:119], v[130:131]
	v_pk_mul_f32 v[120:121], v[120:121], v[130:131]
	v_exp_f32_e32 v114, v114
	v_exp_f32_e32 v115, v115
	v_exp_f32_e32 v116, v116
	v_exp_f32_e32 v117, v117
	v_exp_f32_e32 v118, v118
	v_exp_f32_e32 v119, v119
	v_exp_f32_e32 v120, v120
	v_exp_f32_e32 v121, v121
	v_pk_add_f32 v[114:115], v[114:115], 1.0 op_sel_hi:[1,0]
	v_pk_add_f32 v[116:117], v[116:117], 1.0 op_sel_hi:[1,0]
	v_pk_add_f32 v[118:119], v[118:119], 1.0 op_sel_hi:[1,0]
	v_pk_add_f32 v[120:121], v[120:121], 1.0 op_sel_hi:[1,0]
	v_rcp_f32_e32 v114, v114
	v_rcp_f32_e32 v115, v115
	v_rcp_f32_e32 v116, v116
	v_rcp_f32_e32 v117, v117
	v_rcp_f32_e32 v118, v118
	v_rcp_f32_e32 v119, v119
	v_rcp_f32_e32 v120, v120
	v_rcp_f32_e32 v121, v121
	v_pk_fma_f32 v[114:115], v[114:115], v[132:133], v[134:135]
	v_pk_fma_f32 v[116:117], v[116:117], v[132:133], v[134:135]
	v_pk_fma_f32 v[118:119], v[118:119], v[132:133], v[134:135]
	v_pk_fma_f32 v[120:121], v[120:121], v[132:133], v[134:135]
	v_cvt_pk_bf16_f32 v20, v114, v115
	v_cvt_pk_bf16_f32 v21, v116, v117
	v_cvt_pk_bf16_f32 v22, v118, v119
	v_cvt_pk_bf16_f32 v23, v120, v121
	global_store_dwordx4 v[124:125], v[20:23], off nt
	v_lshl_add_u64 v[124:125], v[126:127], 0, v[124:125]
	s_waitcnt vmcnt(15)
	v_lshlrev_b32_e32 v114, 16, v32
	v_and_b32_e32 v115, 0xffff0000, v32
	v_lshlrev_b32_e32 v116, 16, v33
	v_and_b32_e32 v117, 0xffff0000, v33
	v_lshlrev_b32_e32 v118, 16, v34
	v_and_b32_e32 v119, 0xffff0000, v34
	v_lshlrev_b32_e32 v120, 16, v35
	v_and_b32_e32 v121, 0xffff0000, v35
	v_pk_mul_f32 v[98:99], v[72:73], v[98:99]
	v_pk_mul_f32 v[100:101], v[74:75], v[100:101]
	v_pk_mul_f32 v[102:103], v[76:77], v[102:103]
	v_pk_mul_f32 v[104:105], v[78:79], v[104:105]
	v_pk_fma_f32 v[98:99], v[80:81], v[106:107], v[98:99]
	v_pk_fma_f32 v[100:101], v[82:83], v[108:109], v[100:101]
	v_pk_fma_f32 v[102:103], v[84:85], v[110:111], v[102:103]
	v_pk_fma_f32 v[104:105], v[86:87], v[112:113], v[104:105]
	v_pk_fma_f32 v[98:99], v[88:89], v[114:115], v[98:99]
	v_pk_fma_f32 v[100:101], v[90:91], v[116:117], v[100:101]
	v_pk_fma_f32 v[102:103], v[92:93], v[118:119], v[102:103]
	v_pk_fma_f32 v[104:105], v[94:95], v[120:121], v[104:105]
	v_pk_mul_f32 v[98:99], v[98:99], v[130:131]
	v_pk_mul_f32 v[100:101], v[100:101], v[130:131]
	v_pk_mul_f32 v[102:103], v[102:103], v[130:131]
	v_pk_mul_f32 v[104:105], v[104:105], v[130:131]
	v_exp_f32_e32 v98, v98
	v_exp_f32_e32 v99, v99
	v_exp_f32_e32 v100, v100
	v_exp_f32_e32 v101, v101
	v_exp_f32_e32 v102, v102
	v_exp_f32_e32 v103, v103
	v_exp_f32_e32 v104, v104
	v_exp_f32_e32 v105, v105
	v_pk_add_f32 v[98:99], v[98:99], 1.0 op_sel_hi:[1,0]
	v_pk_add_f32 v[100:101], v[100:101], 1.0 op_sel_hi:[1,0]
	v_pk_add_f32 v[102:103], v[102:103], 1.0 op_sel_hi:[1,0]
	v_pk_add_f32 v[104:105], v[104:105], 1.0 op_sel_hi:[1,0]
	v_rcp_f32_e32 v98, v98
	v_rcp_f32_e32 v99, v99
	v_rcp_f32_e32 v100, v100
	v_rcp_f32_e32 v101, v101
	v_rcp_f32_e32 v102, v102
	v_rcp_f32_e32 v103, v103
	v_rcp_f32_e32 v104, v104
	v_rcp_f32_e32 v105, v105
	v_pk_fma_f32 v[98:99], v[98:99], v[132:133], v[134:135]
	v_pk_fma_f32 v[100:101], v[100:101], v[132:133], v[134:135]
	v_pk_fma_f32 v[102:103], v[102:103], v[132:133], v[134:135]
	v_pk_fma_f32 v[104:105], v[104:105], v[132:133], v[134:135]
	v_cvt_pk_bf16_f32 v24, v98, v99
	v_cvt_pk_bf16_f32 v25, v100, v101
	v_cvt_pk_bf16_f32 v26, v102, v103
	v_cvt_pk_bf16_f32 v27, v104, v105
	global_store_dwordx4 v[124:125], v[24:27], off nt
	v_lshl_add_u64 v[124:125], v[126:127], 0, v[124:125]
	s_waitcnt vmcnt(15)
; DEV float lo_bf(unsigned u) { return __uint_as_float(u << 16); }
; DEV float hi_bf(unsigned u) { return __uint_as_float(u & 0xffff0000u); }
; DEV float sigmoidf_(float x) { return __builtin_amdgcn_rcpf(1.f + __expf(-x)); }
; DEV void shift_tile(const Params& p, int l, int tile) {
;     ...
; #pragma unroll
;   for (int i = 0; i < 16; ++i) {
;     const int row = rb + i;
;     const u32x4 pv = rows[i], cu = rows[i + 1], nx = rows[i + 2];
;     float y[8];
; #pragma unroll
;     for (int q = 0; q < 4; ++q) {
;       y[2 * q] = w0[2 * q] * lo_bf(pv[q]) + w1[2 * q] * lo_bf(cu[q]) + w2[2 * q] * lo_bf(nx[q]);
;       y[2 * q + 1] = w0[2 * q + 1] * hi_bf(pv[q]) + w1[2 * q + 1] * hi_bf(cu[q]) + w2[2 * q + 1] * hi_bf(nx[q]);
;     }
;     if (act == 1) {
; #pragma unroll
;       for (int j = 0; j < 8; ++j) y[j] = 1.f - 2.f * __builtin_amdgcn_rcpf(1.f + __expf(2.f * y[j]));
;     } else if (act == 2) {
; #pragma unroll
;       for (int j = 0; j < 8; ++j) y[j] = sigmoidf_(y[j]);
;     }
;     u32x4 o;
;     o[0] = pk2(y[0], y[1]); o[1] = pk2(y[2], y[3]); o[2] = pk2(y[4], y[5]); o[3] = pk2(y[6], y[7]);
;     if (col < 1536) *(u32x4*)(ZRS + (size_t)row * 1536 + col) = o;
	v_lshlrev_b32_e32 v98, 16, v36
	v_and_b32_e32 v99, 0xffff0000, v36
	v_lshlrev_b32_e32 v100, 16, v37
	v_and_b32_e32 v101, 0xffff0000, v37
	v_lshlrev_b32_e32 v102, 16, v38
	v_and_b32_e32 v103, 0xffff0000, v38
	v_lshlrev_b32_e32 v104, 16, v39
	v_and_b32_e32 v105, 0xffff0000, v39
	v_pk_mul_f32 v[106:107], v[72:73], v[106:107]
	v_pk_mul_f32 v[108:109], v[74:75], v[108:109]
	v_pk_mul_f32 v[110:111], v[76:77], v[110:111]
	v_pk_mul_f32 v[112:113], v[78:79], v[112:113]
	v_pk_fma_f32 v[106:107], v[80:81], v[114:115], v[106:107]
	v_pk_fma_f32 v[108:109], v[82:83], v[116:117], v[108:109]
	v_pk_fma_f32 v[110:111], v[84:85], v[118:119], v[110:111]
	v_pk_fma_f32 v[112:113], v[86:87], v[120:121], v[112:113]
	v_pk_fma_f32 v[106:107], v[88:89], v[98:99], v[106:107]
	v_pk_fma_f32 v[108:109], v[90:91], v[100:101], v[108:109]
	v_pk_fma_f32 v[110:111], v[92:93], v[102:103], v[110:111]
	v_pk_fma_f32 v[112:113], v[94:95], v[104:105], v[112:113]
	v_pk_mul_f32 v[106:107], v[106:107], v[130:131]
	v_pk_mul_f32 v[108:109], v[108:109], v[130:131]
	v_pk_mul_f32 v[110:111], v[110:111], v[130:131]
	v_pk_mul_f32 v[112:113], v[112:113], v[130:131]
	v_exp_f32_e32 v106, v106
	v_exp_f32_e32 v107, v107
	v_exp_f32_e32 v108, v108
	v_exp_f32_e32 v109, v109
	v_exp_f32_e32 v110, v110
	v_exp_f32_e32 v111, v111
	v_exp_f32_e32 v112, v112
	v_exp_f32_e32 v113, v113
	v_pk_add_f32 v[106:107], v[106:107], 1.0 op_sel_hi:[1,0]
	v_pk_add_f32 v[108:109], v[108:109], 1.0 op_sel_hi:[1,0]
	v_pk_add_f32 v[110:111], v[110:111], 1.0 op_sel_hi:[1,0]
	v_pk_add_f32 v[112:113], v[112:113], 1.0 op_sel_hi:[1,0]
	v_rcp_f32_e32 v106, v106
	v_rcp_f32_e32 v107, v107
	v_rcp_f32_e32 v108, v108
	v_rcp_f32_e32 v109, v109
	v_rcp_f32_e32 v110, v110
	v_rcp_f32_e32 v111, v111
	v_rcp_f32_e32 v112, v112
	v_rcp_f32_e32 v113, v113
	v_pk_fma_f32 v[106:107], v[106:107], v[132:133], v[134:135]
	v_pk_fma_f32 v[108:109], v[108:109], v[132:133], v[134:135]
	v_pk_fma_f32 v[110:111], v[110:111], v[132:133], v[134:135]
	v_pk_fma_f32 v[112:113], v[112:113], v[132:133], v[134:135]
	v_cvt_pk_bf16_f32 v28, v106, v107
	v_cvt_pk_bf16_f32 v29, v108, v109
	v_cvt_pk_bf16_f32 v30, v110, v111
	v_cvt_pk_bf16_f32 v31, v112, v113
	global_store_dwordx4 v[124:125], v[28:31], off nt
	v_lshl_add_u64 v[124:125], v[126:127], 0, v[124:125]
	s_waitcnt vmcnt(15)
	v_lshlrev_b32_e32 v106, 16, v40
	v_and_b32_e32 v107, 0xffff0000, v40
	v_lshlrev_b32_e32 v108, 16, v41
	v_and_b32_e32 v109, 0xffff0000, v41
	v_lshlrev_b32_e32 v110, 16, v42
	v_and_b32_e32 v111, 0xffff0000, v42
	v_lshlrev_b32_e32 v112, 16, v43
	v_and_b32_e32 v113, 0xffff0000, v43
	v_pk_mul_f32 v[114:115], v[72:73], v[114:115]
	v_pk_mul_f32 v[116:117], v[74:75], v[116:117]
	v_pk_mul_f32 v[118:119], v[76:77], v[118:119]
	v_pk_mul_f32 v[120:121], v[78:79], v[120:121]
	v_pk_fma_f32 v[114:115], v[80:81], v[98:99], v[114:115]
	v_pk_fma_f32 v[116:117], v[82:83], v[100:101], v[116:117]
	v_pk_fma_f32 v[118:119], v[84:85], v[102:103], v[118:119]
	v_pk_fma_f32 v[120:121], v[86:87], v[104:105], v[120:121]
	v_pk_fma_f32 v[114:115], v[88:89], v[106:107], v[114:115]
	v_pk_fma_f32 v[116:117], v[90:91], v[108:109], v[116:117]
	v_pk_fma_f32 v[118:119], v[92:93], v[110:111], v[118:119]
	v_pk_fma_f32 v[120:121], v[94:95], v[112:113], v[120:121]
	v_pk_mul_f32 v[114:115], v[114:115], v[130:131]
	v_pk_mul_f32 v[116:117], v[116:117], v[130:131]
	v_pk_mul_f32 v[118:119], v[118:119], v[130:131]
	v_pk_mul_f32 v[120:121], v[120:121], v[130:131]
	v_exp_f32_e32 v114, v114
	v_exp_f32_e32 v115, v115
	v_exp_f32_e32 v116, v116
	v_exp_f32_e32 v117, v117
	v_exp_f32_e32 v118, v118
	v_exp_f32_e32 v119, v119
	v_exp_f32_e32 v120, v120
	v_exp_f32_e32 v121, v121
	v_pk_add_f32 v[114:115], v[114:115], 1.0 op_sel_hi:[1,0]
	v_pk_add_f32 v[116:117], v[116:117], 1.0 op_sel_hi:[1,0]
	v_pk_add_f32 v[118:119], v[118:119], 1.0 op_sel_hi:[1,0]
	v_pk_add_f32 v[120:121], v[120:121], 1.0 op_sel_hi:[1,0]
	v_rcp_f32_e32 v114, v114
	v_rcp_f32_e32 v115, v115
	v_rcp_f32_e32 v116, v116
	v_rcp_f32_e32 v117, v117
	v_rcp_f32_e32 v118, v118
	v_rcp_f32_e32 v119, v119
	v_rcp_f32_e32 v120, v120
	v_rcp_f32_e32 v121, v121
	v_pk_fma_f32 v[114:115], v[114:115], v[132:133], v[134:135]
	v_pk_fma_f32 v[116:117], v[116:117], v[132:133], v[134:135]
	v_pk_fma_f32 v[118:119], v[118:119], v[132:133], v[134:135]
	v_pk_fma_f32 v[120:121], v[120:121], v[132:133], v[134:135]
	v_cvt_pk_bf16_f32 v32, v114, v115
	v_cvt_pk_bf16_f32 v33, v116, v117
	v_cvt_pk_bf16_f32 v34, v118, v119
	v_cvt_pk_bf16_f32 v35, v120, v121
	global_store_dwordx4 v[124:125], v[32:35], off nt
	v_lshl_add_u64 v[124:125], v[126:127], 0, v[124:125]
	s_waitcnt vmcnt(15)
; DEV float lo_bf(unsigned u) { return __uint_as_float(u << 16); }
; DEV float hi_bf(unsigned u) { return __uint_as_float(u & 0xffff0000u); }
; DEV float sigmoidf_(float x) { return __builtin_amdgcn_rcpf(1.f + __expf(-x)); }
; DEV void shift_tile(const Params& p, int l, int tile) {
;     ...
;   const int act = (col >= 1536 && col < 1664) ? 1 : (col >= 1792 ? 2 : 0);
; #pragma unroll
;   for (int i = 0; i < 16; ++i) {
;     const int row = rb + i;
;     const u32x4 pv = rows[i], cu = rows[i + 1], nx = rows[i + 2];
;     float y[8];
; #pragma unroll
;     for (int q = 0; q < 4; ++q) {
;       y[2 * q] = w0[2 * q] * lo_bf(pv[q]) + w1[2 * q] * lo_bf(cu[q]) + w2[2 * q] * lo_bf(nx[q]);
;       y[2 * q + 1] = w0[2 * q + 1] * hi_bf(pv[q]) + w1[2 * q + 1] * hi_bf(cu[q]) + w2[2 * q + 1] * hi_bf(nx[q]);
;     }
;     if (act == 1) {
; #pragma unroll
;       for (int j = 0; j < 8; ++j) y[j] = 1.f - 2.f * __builtin_amdgcn_rcpf(1.f + __expf(2.f * y[j]));
;     } else if (act == 2) {
; #pragma unroll
;       for (int j = 0; j < 8; ++j) y[j] = sigmoidf_(y[j]);
;     }
;     u32x4 o;
;     o[0] = pk2(y[0], y[1]); o[1] = pk2(y[2], y[3]); o[2] = pk2(y[4], y[5]); o[3] = pk2(y[6], y[7]);
;     if (col < 1536) *(u32x4*)(ZRS + (size_t)row * 1536 + col) = o;
;     else if (col < 1792) *(u32x4*)((bf16_t*)(p.ws + O_LIN) + (size_t)row * 256 + (col - 1536)) = o;
;     else *(u32x4*)((bf16_t*)(p.ws + O_GIN) + (size_t)row * 128 + (col - 1792)) = o;
;   }
	v_lshlrev_b32_e32 v114, 16, v44
	v_and_b32_e32 v115, 0xffff0000, v44
	v_lshlrev_b32_e32 v116, 16, v45
	v_and_b32_e32 v117, 0xffff0000, v45
	v_lshlrev_b32_e32 v118, 16, v46
	v_and_b32_e32 v119, 0xffff0000, v46
	v_lshlrev_b32_e32 v120, 16, v47
	v_and_b32_e32 v121, 0xffff0000, v47
	v_pk_mul_f32 v[98:99], v[72:73], v[98:99]
	v_pk_mul_f32 v[100:101], v[74:75], v[100:101]
	v_pk_mul_f32 v[102:103], v[76:77], v[102:103]
	v_pk_mul_f32 v[104:105], v[78:79], v[104:105]
	v_pk_fma_f32 v[98:99], v[80:81], v[106:107], v[98:99]
	v_pk_fma_f32 v[100:101], v[82:83], v[108:109], v[100:101]
	v_pk_fma_f32 v[102:103], v[84:85], v[110:111], v[102:103]
	v_pk_fma_f32 v[104:105], v[86:87], v[112:113], v[104:105]
	v_pk_fma_f32 v[98:99], v[88:89], v[114:115], v[98:99]
	v_pk_fma_f32 v[100:101], v[90:91], v[116:117], v[100:101]
	v_pk_fma_f32 v[102:103], v[92:93], v[118:119], v[102:103]
	v_pk_fma_f32 v[104:105], v[94:95], v[120:121], v[104:105]
	v_pk_mul_f32 v[98:99], v[98:99], v[130:131]
	v_pk_mul_f32 v[100:101], v[100:101], v[130:131]
	v_pk_mul_f32 v[102:103], v[102:103], v[130:131]
	v_pk_mul_f32 v[104:105], v[104:105], v[130:131]
	v_exp_f32_e32 v98, v98
	v_exp_f32_e32 v99, v99
	v_exp_f32_e32 v100, v100
	v_exp_f32_e32 v101, v101
	v_exp_f32_e32 v102, v102
	v_exp_f32_e32 v103, v103
	v_exp_f32_e32 v104, v104
	v_exp_f32_e32 v105, v105
	v_pk_add_f32 v[98:99], v[98:99], 1.0 op_sel_hi:[1,0]
	v_pk_add_f32 v[100:101], v[100:101], 1.0 op_sel_hi:[1,0]
	v_pk_add_f32 v[102:103], v[102:103], 1.0 op_sel_hi:[1,0]
	v_pk_add_f32 v[104:105], v[104:105], 1.0 op_sel_hi:[1,0]
	v_rcp_f32_e32 v98, v98
	v_rcp_f32_e32 v99, v99
	v_rcp_f32_e32 v100, v100
	v_rcp_f32_e32 v101, v101
	v_rcp_f32_e32 v102, v102
	v_rcp_f32_e32 v103, v103
	v_rcp_f32_e32 v104, v104
	v_rcp_f32_e32 v105, v105
	v_pk_fma_f32 v[98:99], v[98:99], v[132:133], v[134:135]
	v_pk_fma_f32 v[100:101], v[100:101], v[132:133], v[134:135]
	v_pk_fma_f32 v[102:103], v[102:103], v[132:133], v[134:135]
	v_pk_fma_f32 v[104:105], v[104:105], v[132:133], v[134:135]
	v_cvt_pk_bf16_f32 v36, v98, v99
	v_cvt_pk_bf16_f32 v37, v100, v101
	v_cvt_pk_bf16_f32 v38, v102, v103
	v_cvt_pk_bf16_f32 v39, v104, v105
	global_store_dwordx4 v[124:125], v[36:39], off nt
	v_lshl_add_u64 v[124:125], v[126:127], 0, v[124:125]
	s_waitcnt vmcnt(15)
	v_lshlrev_b32_e32 v98, 16, v48
	v_and_b32_e32 v99, 0xffff0000, v48
	v_lshlrev_b32_e32 v100, 16, v49
	v_and_b32_e32 v101, 0xffff0000, v49
	v_lshlrev_b32_e32 v102, 16, v50
	v_and_b32_e32 v103, 0xffff0000, v50
	v_lshlrev_b32_e32 v104, 16, v51
	v_and_b32_e32 v105, 0xffff0000, v51
	v_pk_mul_f32 v[106:107], v[72:73], v[106:107]
	v_pk_mul_f32 v[108:109], v[74:75], v[108:109]
	v_pk_mul_f32 v[110:111], v[76:77], v[110:111]
	v_pk_mul_f32 v[112:113], v[78:79], v[112:113]
	v_pk_fma_f32 v[106:107], v[80:81], v[114:115], v[106:107]
	v_pk_fma_f32 v[108:109], v[82:83], v[116:117], v[108:109]
	v_pk_fma_f32 v[110:111], v[84:85], v[118:119], v[110:111]
	v_pk_fma_f32 v[112:113], v[86:87], v[120:121], v[112:113]
	v_pk_fma_f32 v[106:107], v[88:89], v[98:99], v[106:107]
	v_pk_fma_f32 v[108:109], v[90:91], v[100:101], v[108:109]
	v_pk_fma_f32 v[110:111], v[92:93], v[102:103], v[110:111]
	v_pk_fma_f32 v[112:113], v[94:95], v[104:105], v[112:113]
	v_pk_mul_f32 v[106:107], v[106:107], v[130:131]
	v_pk_mul_f32 v[108:109], v[108:109], v[130:131]
	v_pk_mul_f32 v[110:111], v[110:111], v[130:131]
	v_pk_mul_f32 v[112:113], v[112:113], v[130:131]
	v_exp_f32_e32 v106, v106
	v_exp_f32_e32 v107, v107
	v_exp_f32_e32 v108, v108
	v_exp_f32_e32 v109, v109
	v_exp_f32_e32 v110, v110
	v_exp_f32_e32 v111, v111
	v_exp_f32_e32 v112, v112
	v_exp_f32_e32 v113, v113
	v_pk_add_f32 v[106:107], v[106:107], 1.0 op_sel_hi:[1,0]
	v_pk_add_f32 v[108:109], v[108:109], 1.0 op_sel_hi:[1,0]
	v_pk_add_f32 v[110:111], v[110:111], 1.0 op_sel_hi:[1,0]
	v_pk_add_f32 v[112:113], v[112:113], 1.0 op_sel_hi:[1,0]
	v_rcp_f32_e32 v106, v106
	v_rcp_f32_e32 v107, v107
	v_rcp_f32_e32 v108, v108
	v_rcp_f32_e32 v109, v109
	v_rcp_f32_e32 v110, v110
	v_rcp_f32_e32 v111, v111
	v_rcp_f32_e32 v112, v112
	v_rcp_f32_e32 v113, v113
	v_pk_fma_f32 v[106:107], v[106:107], v[132:133], v[134:135]
	v_pk_fma_f32 v[108:109], v[108:109], v[132:133], v[134:135]
	v_pk_fma_f32 v[110:111], v[110:111], v[132:133], v[134:135]
	v_pk_fma_f32 v[112:113], v[112:113], v[132:133], v[134:135]
	v_cvt_pk_bf16_f32 v40, v106, v107
	v_cvt_pk_bf16_f32 v41, v108, v109
	v_cvt_pk_bf16_f32 v42, v110, v111
	v_cvt_pk_bf16_f32 v43, v112, v113
	global_store_dwordx4 v[124:125], v[40:43], off nt
	v_lshl_add_u64 v[124:125], v[126:127], 0, v[124:125]
	s_waitcnt vmcnt(15)
; DEV float lo_bf(unsigned u) { return __uint_as_float(u << 16); }
; DEV float hi_bf(unsigned u) { return __uint_as_float(u & 0xffff0000u); }
; DEV float sigmoidf_(float x) { return __builtin_amdgcn_rcpf(1.f + __expf(-x)); }
; DEV void shift_tile(const Params& p, int l, int tile) {
;     ...
;   const int act = (col >= 1536 && col < 1664) ? 1 : (col >= 1792 ? 2 : 0);
; #pragma unroll
;   for (int i = 0; i < 16; ++i) {
;     const int row = rb + i;
;     const u32x4 pv = rows[i], cu = rows[i + 1], nx = rows[i + 2];
;     float y[8];
; #pragma unroll
;     for (int q = 0; q < 4; ++q) {
;       y[2 * q] = w0[2 * q] * lo_bf(pv[q]) + w1[2 * q] * lo_bf(cu[q]) + w2[2 * q] * lo_bf(nx[q]);
;       y[2 * q + 1] = w0[2 * q + 1] * hi_bf(pv[q]) + w1[2 * q + 1] * hi_bf(cu[q]) + w2[2 * q + 1] * hi_bf(nx[q]);
;     }
;     if (act == 1) {
; #pragma unroll
;       for (int j = 0; j < 8; ++j) y[j] = 1.f - 2.f * __builtin_amdgcn_rcpf(1.f + __expf(2.f * y[j]));
;     } else if (act == 2) {
; #pragma unroll
;       for (int j = 0; j < 8; ++j) y[j] = sigmoidf_(y[j]);
;     }
;     u32x4 o;
;     o[0] = pk2(y[0], y[1]); o[1] = pk2(y[2], y[3]); o[2] = pk2(y[4], y[5]); o[3] = pk2(y[6], y[7]);
;     if (col < 1536) *(u32x4*)(ZRS + (size_t)row * 1536 + col) = o;
;     else if (col < 1792) *(u32x4*)((bf16_t*)(p.ws + O_LIN) + (size_t)row * 256 + (col - 1536)) = o;
;     else *(u32x4*)((bf16_t*)(p.ws + O_GIN) + (size_t)row * 128 + (col - 1792)) = o;
;   }
	v_lshlrev_b32_e32 v106, 16, v52
	v_and_b32_e32 v107, 0xffff0000, v52
	v_lshlrev_b32_e32 v108, 16, v53
	v_and_b32_e32 v109, 0xffff0000, v53
	v_lshlrev_b32_e32 v110, 16, v54
	v_and_b32_e32 v111, 0xffff0000, v54
	v_lshlrev_b32_e32 v112, 16, v55
	v_and_b32_e32 v113, 0xffff0000, v55
	v_pk_mul_f32 v[114:115], v[72:73], v[114:115]
	v_pk_mul_f32 v[116:117], v[74:75], v[116:117]
	v_pk_mul_f32 v[118:119], v[76:77], v[118:119]
	v_pk_mul_f32 v[120:121], v[78:79], v[120:121]
	v_pk_fma_f32 v[114:115], v[80:81], v[98:99], v[114:115]
	v_pk_fma_f32 v[116:117], v[82:83], v[100:101], v[116:117]
	v_pk_fma_f32 v[118:119], v[84:85], v[102:103], v[118:119]
	v_pk_fma_f32 v[120:121], v[86:87], v[104:105], v[120:121]
	v_pk_fma_f32 v[114:115], v[88:89], v[106:107], v[114:115]
	v_pk_fma_f32 v[116:117], v[90:91], v[108:109], v[116:117]
	v_pk_fma_f32 v[118:119], v[92:93], v[110:111], v[118:119]
	v_pk_fma_f32 v[120:121], v[94:95], v[112:113], v[120:121]
	v_pk_mul_f32 v[114:115], v[114:115], v[130:131]
	v_pk_mul_f32 v[116:117], v[116:117], v[130:131]
	v_pk_mul_f32 v[118:119], v[118:119], v[130:131]
	v_pk_mul_f32 v[120:121], v[120:121], v[130:131]
	v_exp_f32_e32 v114, v114
	v_exp_f32_e32 v115, v115
	v_exp_f32_e32 v116, v116
	v_exp_f32_e32 v117, v117
	v_exp_f32_e32 v118, v118
	v_exp_f32_e32 v119, v119
	v_exp_f32_e32 v120, v120
	v_exp_f32_e32 v121, v121
	v_pk_add_f32 v[114:115], v[114:115], 1.0 op_sel_hi:[1,0]
	v_pk_add_f32 v[116:117], v[116:117], 1.0 op_sel_hi:[1,0]
	v_pk_add_f32 v[118:119], v[118:119], 1.0 op_sel_hi:[1,0]
	v_pk_add_f32 v[120:121], v[120:121], 1.0 op_sel_hi:[1,0]
	v_rcp_f32_e32 v114, v114
	v_rcp_f32_e32 v115, v115
	v_rcp_f32_e32 v116, v116
	v_rcp_f32_e32 v117, v117
	v_rcp_f32_e32 v118, v118
	v_rcp_f32_e32 v119, v119
	v_rcp_f32_e32 v120, v120
	v_rcp_f32_e32 v121, v121
	v_pk_fma_f32 v[114:115], v[114:115], v[132:133], v[134:135]
	v_pk_fma_f32 v[116:117], v[116:117], v[132:133], v[134:135]
	v_pk_fma_f32 v[118:119], v[118:119], v[132:133], v[134:135]
	v_pk_fma_f32 v[120:121], v[120:121], v[132:133], v[134:135]
	v_cvt_pk_bf16_f32 v44, v114, v115
	v_cvt_pk_bf16_f32 v45, v116, v117
	v_cvt_pk_bf16_f32 v46, v118, v119
	v_cvt_pk_bf16_f32 v47, v120, v121
	global_store_dwordx4 v[124:125], v[44:47], off nt
	v_lshl_add_u64 v[124:125], v[126:127], 0, v[124:125]
	s_waitcnt vmcnt(15)
	v_lshlrev_b32_e32 v114, 16, v56
	v_and_b32_e32 v115, 0xffff0000, v56
	v_lshlrev_b32_e32 v116, 16, v57
	v_and_b32_e32 v117, 0xffff0000, v57
	v_lshlrev_b32_e32 v118, 16, v58
	v_and_b32_e32 v119, 0xffff0000, v58
	v_lshlrev_b32_e32 v120, 16, v59
	v_and_b32_e32 v121, 0xffff0000, v59
	v_pk_mul_f32 v[98:99], v[72:73], v[98:99]
	v_pk_mul_f32 v[100:101], v[74:75], v[100:101]
	v_pk_mul_f32 v[102:103], v[76:77], v[102:103]
	v_pk_mul_f32 v[104:105], v[78:79], v[104:105]
	v_pk_fma_f32 v[98:99], v[80:81], v[106:107], v[98:99]
	v_pk_fma_f32 v[100:101], v[82:83], v[108:109], v[100:101]
	v_pk_fma_f32 v[102:103], v[84:85], v[110:111], v[102:103]
	v_pk_fma_f32 v[104:105], v[86:87], v[112:113], v[104:105]
	v_pk_fma_f32 v[98:99], v[88:89], v[114:115], v[98:99]
	v_pk_fma_f32 v[100:101], v[90:91], v[116:117], v[100:101]
	v_pk_fma_f32 v[102:103], v[92:93], v[118:119], v[102:103]
	v_pk_fma_f32 v[104:105], v[94:95], v[120:121], v[104:105]
	v_pk_mul_f32 v[98:99], v[98:99], v[130:131]
	v_pk_mul_f32 v[100:101], v[100:101], v[130:131]
	v_pk_mul_f32 v[102:103], v[102:103], v[130:131]
	v_pk_mul_f32 v[104:105], v[104:105], v[130:131]
	v_exp_f32_e32 v98, v98
	v_exp_f32_e32 v99, v99
	v_exp_f32_e32 v100, v100
	v_exp_f32_e32 v101, v101
	v_exp_f32_e32 v102, v102
	v_exp_f32_e32 v103, v103
	v_exp_f32_e32 v104, v104
	v_exp_f32_e32 v105, v105
	v_pk_add_f32 v[98:99], v[98:99], 1.0 op_sel_hi:[1,0]
	v_pk_add_f32 v[100:101], v[100:101], 1.0 op_sel_hi:[1,0]
	v_pk_add_f32 v[102:103], v[102:103], 1.0 op_sel_hi:[1,0]
	v_pk_add_f32 v[104:105], v[104:105], 1.0 op_sel_hi:[1,0]
	v_rcp_f32_e32 v98, v98
	v_rcp_f32_e32 v99, v99
	v_rcp_f32_e32 v100, v100
	v_rcp_f32_e32 v101, v101
	v_rcp_f32_e32 v102, v102
	v_rcp_f32_e32 v103, v103
	v_rcp_f32_e32 v104, v104
	v_rcp_f32_e32 v105, v105
	v_pk_fma_f32 v[98:99], v[98:99], v[132:133], v[134:135]
	v_pk_fma_f32 v[100:101], v[100:101], v[132:133], v[134:135]
	v_pk_fma_f32 v[102:103], v[102:103], v[132:133], v[134:135]
	v_pk_fma_f32 v[104:105], v[104:105], v[132:133], v[134:135]
	v_cvt_pk_bf16_f32 v48, v98, v99
	v_cvt_pk_bf16_f32 v49, v100, v101
	v_cvt_pk_bf16_f32 v50, v102, v103
	v_cvt_pk_bf16_f32 v51, v104, v105
	global_store_dwordx4 v[124:125], v[48:51], off nt
	v_lshl_add_u64 v[124:125], v[126:127], 0, v[124:125]
	s_waitcnt vmcnt(15)
; DEV float lo_bf(unsigned u) { return __uint_as_float(u << 16); }
; DEV float hi_bf(unsigned u) { return __uint_as_float(u & 0xffff0000u); }
; DEV float sigmoidf_(float x) { return __builtin_amdgcn_rcpf(1.f + __expf(-x)); }
; DEV void shift_tile(const Params& p, int l, int tile) {
;     ...
;   const int act = (col >= 1536 && col < 1664) ? 1 : (col >= 1792 ? 2 : 0);
; #pragma unroll
;   for (int i = 0; i < 16; ++i) {
;     const int row = rb + i;
;     const u32x4 pv = rows[i], cu = rows[i + 1], nx = rows[i + 2];
;     float y[8];
; #pragma unroll
;     for (int q = 0; q < 4; ++q) {
;       y[2 * q] = w0[2 * q] * lo_bf(pv[q]) + w1[2 * q] * lo_bf(cu[q]) + w2[2 * q] * lo_bf(nx[q]);
;       y[2 * q + 1] = w0[2 * q + 1] * hi_bf(pv[q]) + w1[2 * q + 1] * hi_bf(cu[q]) + w2[2 * q + 1] * hi_bf(nx[q]);
;     }
;     if (act == 1) {
; #pragma unroll
;       for (int j = 0; j < 8; ++j) y[j] = 1.f - 2.f * __builtin_amdgcn_rcpf(1.f + __expf(2.f * y[j]));
;     } else if (act == 2) {
; #pragma unroll
;       for (int j = 0; j < 8; ++j) y[j] = sigmoidf_(y[j]);
;     }
;     u32x4 o;
;     o[0] = pk2(y[0], y[1]); o[1] = pk2(y[2], y[3]); o[2] = pk2(y[4], y[5]); o[3] = pk2(y[6], y[7]);
;     if (col < 1536) *(u32x4*)(ZRS + (size_t)row * 1536 + col) = o;
;     else if (col < 1792) *(u32x4*)((bf16_t*)(p.ws + O_LIN) + (size_t)row * 256 + (col - 1536)) = o;
;     else *(u32x4*)((bf16_t*)(p.ws + O_GIN) + (size_t)row * 128 + (col - 1792)) = o;
;   }
	v_lshlrev_b32_e32 v98, 16, v60
	v_and_b32_e32 v99, 0xffff0000, v60
	v_lshlrev_b32_e32 v100, 16, v61
	v_and_b32_e32 v101, 0xffff0000, v61
	v_lshlrev_b32_e32 v102, 16, v62
	v_and_b32_e32 v103, 0xffff0000, v62
	v_lshlrev_b32_e32 v104, 16, v63
	v_and_b32_e32 v105, 0xffff0000, v63
	v_pk_mul_f32 v[106:107], v[72:73], v[106:107]
	v_pk_mul_f32 v[108:109], v[74:75], v[108:109]
	v_pk_mul_f32 v[110:111], v[76:77], v[110:111]
	v_pk_mul_f32 v[112:113], v[78:79], v[112:113]
	v_pk_fma_f32 v[106:107], v[80:81], v[114:115], v[106:107]
	v_pk_fma_f32 v[108:109], v[82:83], v[116:117], v[108:109]
	v_pk_fma_f32 v[110:111], v[84:85], v[118:119], v[110:111]
	v_pk_fma_f32 v[112:113], v[86:87], v[120:121], v[112:113]
	v_pk_fma_f32 v[106:107], v[88:89], v[98:99], v[106:107]
	v_pk_fma_f32 v[108:109], v[90:91], v[100:101], v[108:109]
	v_pk_fma_f32 v[110:111], v[92:93], v[102:103], v[110:111]
	v_pk_fma_f32 v[112:113], v[94:95], v[104:105], v[112:113]
	v_pk_mul_f32 v[106:107], v[106:107], v[130:131]
	v_pk_mul_f32 v[108:109], v[108:109], v[130:131]
	v_pk_mul_f32 v[110:111], v[110:111], v[130:131]
	v_pk_mul_f32 v[112:113], v[112:113], v[130:131]
	v_exp_f32_e32 v106, v106
	v_exp_f32_e32 v107, v107
	v_exp_f32_e32 v108, v108
	v_exp_f32_e32 v109, v109
	v_exp_f32_e32 v110, v110
	v_exp_f32_e32 v111, v111
	v_exp_f32_e32 v112, v112
	v_exp_f32_e32 v113, v113
	v_pk_add_f32 v[106:107], v[106:107], 1.0 op_sel_hi:[1,0]
	v_pk_add_f32 v[108:109], v[108:109], 1.0 op_sel_hi:[1,0]
	v_pk_add_f32 v[110:111], v[110:111], 1.0 op_sel_hi:[1,0]
	v_pk_add_f32 v[112:113], v[112:113], 1.0 op_sel_hi:[1,0]
	v_rcp_f32_e32 v106, v106
	v_rcp_f32_e32 v107, v107
	v_rcp_f32_e32 v108, v108
	v_rcp_f32_e32 v109, v109
	v_rcp_f32_e32 v110, v110
	v_rcp_f32_e32 v111, v111
	v_rcp_f32_e32 v112, v112
	v_rcp_f32_e32 v113, v113
	v_pk_fma_f32 v[106:107], v[106:107], v[132:133], v[134:135]
	v_pk_fma_f32 v[108:109], v[108:109], v[132:133], v[134:135]
	v_pk_fma_f32 v[110:111], v[110:111], v[132:133], v[134:135]
	v_pk_fma_f32 v[112:113], v[112:113], v[132:133], v[134:135]
	v_cvt_pk_bf16_f32 v52, v106, v107
	v_cvt_pk_bf16_f32 v53, v108, v109
	v_cvt_pk_bf16_f32 v54, v110, v111
	v_cvt_pk_bf16_f32 v55, v112, v113
	global_store_dwordx4 v[124:125], v[52:55], off nt
	v_lshl_add_u64 v[124:125], v[126:127], 0, v[124:125]
	s_waitcnt vmcnt(15)
	v_lshlrev_b32_e32 v106, 16, v64
	v_and_b32_e32 v107, 0xffff0000, v64
	v_lshlrev_b32_e32 v108, 16, v65
	v_and_b32_e32 v109, 0xffff0000, v65
	v_lshlrev_b32_e32 v110, 16, v66
	v_and_b32_e32 v111, 0xffff0000, v66
	v_lshlrev_b32_e32 v112, 16, v67
	v_and_b32_e32 v113, 0xffff0000, v67
	v_pk_mul_f32 v[114:115], v[72:73], v[114:115]
	v_pk_mul_f32 v[116:117], v[74:75], v[116:117]
	v_pk_mul_f32 v[118:119], v[76:77], v[118:119]
	v_pk_mul_f32 v[120:121], v[78:79], v[120:121]
	v_pk_fma_f32 v[114:115], v[80:81], v[98:99], v[114:115]
	v_pk_fma_f32 v[116:117], v[82:83], v[100:101], v[116:117]
	v_pk_fma_f32 v[118:119], v[84:85], v[102:103], v[118:119]
	v_pk_fma_f32 v[120:121], v[86:87], v[104:105], v[120:121]
	v_pk_fma_f32 v[114:115], v[88:89], v[106:107], v[114:115]
	v_pk_fma_f32 v[116:117], v[90:91], v[108:109], v[116:117]
	v_pk_fma_f32 v[118:119], v[92:93], v[110:111], v[118:119]
	v_pk_fma_f32 v[120:121], v[94:95], v[112:113], v[120:121]
	v_pk_mul_f32 v[114:115], v[114:115], v[130:131]
	v_pk_mul_f32 v[116:117], v[116:117], v[130:131]
	v_pk_mul_f32 v[118:119], v[118:119], v[130:131]
	v_pk_mul_f32 v[120:121], v[120:121], v[130:131]
	v_exp_f32_e32 v114, v114
	v_exp_f32_e32 v115, v115
	v_exp_f32_e32 v116, v116
	v_exp_f32_e32 v117, v117
	v_exp_f32_e32 v118, v118
	v_exp_f32_e32 v119, v119
	v_exp_f32_e32 v120, v120
	v_exp_f32_e32 v121, v121
	v_pk_add_f32 v[114:115], v[114:115], 1.0 op_sel_hi:[1,0]
	v_pk_add_f32 v[116:117], v[116:117], 1.0 op_sel_hi:[1,0]
	v_pk_add_f32 v[118:119], v[118:119], 1.0 op_sel_hi:[1,0]
	v_pk_add_f32 v[120:121], v[120:121], 1.0 op_sel_hi:[1,0]
	v_rcp_f32_e32 v114, v114
	v_rcp_f32_e32 v115, v115
	v_rcp_f32_e32 v116, v116
	v_rcp_f32_e32 v117, v117
	v_rcp_f32_e32 v118, v118
	v_rcp_f32_e32 v119, v119
	v_rcp_f32_e32 v120, v120
	v_rcp_f32_e32 v121, v121
	v_pk_fma_f32 v[114:115], v[114:115], v[132:133], v[134:135]
	v_pk_fma_f32 v[116:117], v[116:117], v[132:133], v[134:135]
	v_pk_fma_f32 v[118:119], v[118:119], v[132:133], v[134:135]
	v_pk_fma_f32 v[120:121], v[120:121], v[132:133], v[134:135]
	v_cvt_pk_bf16_f32 v56, v114, v115
	v_cvt_pk_bf16_f32 v57, v116, v117
	v_cvt_pk_bf16_f32 v58, v118, v119
	v_cvt_pk_bf16_f32 v59, v120, v121
	global_store_dwordx4 v[124:125], v[56:59], off nt
	v_lshl_add_u64 v[124:125], v[126:127], 0, v[124:125]
	s_waitcnt vmcnt(15)
	v_lshlrev_b32_e32 v114, 16, v68
	v_and_b32_e32 v115, 0xffff0000, v68
	v_lshlrev_b32_e32 v116, 16, v69
	v_and_b32_e32 v117, 0xffff0000, v69
	v_lshlrev_b32_e32 v118, 16, v70
	v_and_b32_e32 v119, 0xffff0000, v70
	v_lshlrev_b32_e32 v120, 16, v71
	v_and_b32_e32 v121, 0xffff0000, v71
	v_pk_mul_f32 v[98:99], v[72:73], v[98:99]
	v_pk_mul_f32 v[100:101], v[74:75], v[100:101]
	v_pk_mul_f32 v[102:103], v[76:77], v[102:103]
	v_pk_mul_f32 v[104:105], v[78:79], v[104:105]
	v_pk_fma_f32 v[98:99], v[80:81], v[106:107], v[98:99]
	v_pk_fma_f32 v[100:101], v[82:83], v[108:109], v[100:101]
	v_pk_fma_f32 v[102:103], v[84:85], v[110:111], v[102:103]
	v_pk_fma_f32 v[104:105], v[86:87], v[112:113], v[104:105]
	v_pk_fma_f32 v[98:99], v[88:89], v[114:115], v[98:99]
	v_pk_fma_f32 v[100:101], v[90:91], v[116:117], v[100:101]
	v_pk_fma_f32 v[102:103], v[92:93], v[118:119], v[102:103]
	v_pk_fma_f32 v[104:105], v[94:95], v[120:121], v[104:105]
	v_pk_mul_f32 v[98:99], v[98:99], v[130:131]
	v_pk_mul_f32 v[100:101], v[100:101], v[130:131]
	v_pk_mul_f32 v[102:103], v[102:103], v[130:131]
	v_pk_mul_f32 v[104:105], v[104:105], v[130:131]
	v_exp_f32_e32 v98, v98
	v_exp_f32_e32 v99, v99
	v_exp_f32_e32 v100, v100
	v_exp_f32_e32 v101, v101
	v_exp_f32_e32 v102, v102
	v_exp_f32_e32 v103, v103
	v_exp_f32_e32 v104, v104
	v_exp_f32_e32 v105, v105
	v_pk_add_f32 v[98:99], v[98:99], 1.0 op_sel_hi:[1,0]
	v_pk_add_f32 v[100:101], v[100:101], 1.0 op_sel_hi:[1,0]
	v_pk_add_f32 v[102:103], v[102:103], 1.0 op_sel_hi:[1,0]
	v_pk_add_f32 v[104:105], v[104:105], 1.0 op_sel_hi:[1,0]
	v_rcp_f32_e32 v98, v98
	v_rcp_f32_e32 v99, v99
	v_rcp_f32_e32 v100, v100
	v_rcp_f32_e32 v101, v101
	v_rcp_f32_e32 v102, v102
	v_rcp_f32_e32 v103, v103
	v_rcp_f32_e32 v104, v104
	v_rcp_f32_e32 v105, v105
	v_pk_fma_f32 v[98:99], v[98:99], v[132:133], v[134:135]
	v_pk_fma_f32 v[100:101], v[100:101], v[132:133], v[134:135]
	v_pk_fma_f32 v[102:103], v[102:103], v[132:133], v[134:135]
	v_pk_fma_f32 v[104:105], v[104:105], v[132:133], v[134:135]
	v_cvt_pk_bf16_f32 v60, v98, v99
	v_cvt_pk_bf16_f32 v61, v100, v101
	v_cvt_pk_bf16_f32 v62, v102, v103
	v_cvt_pk_bf16_f32 v63, v104, v105
	global_store_dwordx4 v[124:125], v[60:63], off nt
